# all six K-loops: the s_barrier that ends each 32-MFMA segment moved 4 MFMAs earlier, so the barrier release latency overlaps the segment's tail MFMAs
# baseline (speedup 1.0000x reference)
; #define PG8_STAGE(bufoff, gbase, voff) do { _Pragma("unroll") for (int _i = 0; _i < 2; ++_i) \
;         __builtin_amdgcn_global_load_lds((const unsigned*)((const char*)(gbase) + (voff)[_i]), (PG8_LAS unsigned*)(lds + (bufoff) + ldsw + _i * 8192), 16, 0, 0); } while (0)
; #define PG8_LDA(dst, b, h) do { _Pragma("unroll") for (int m = 0; m < 4; ++m) _Pragma("unroll") for (int k = 0; k < 2; ++k) dst[m][k] = *(const PG8_LAS bf16x8*)(lds + PG8_SA(b, h) + aoff + m * 2048 + k * 1024); } while (0)
; #define PG8_LDB(dst, b, h) do { _Pragma("unroll") for (int n = 0; n < 2; ++n) _Pragma("unroll") for (int k = 0; k < 2; ++k) dst[n][k] = *(const PG8_LAS bf16x8*)(lds + PG8_SB(b, h) + boff + n * 2048 + k * 1024); } while (0)
; #define PG8_MMA(ai, bj, At, Bt) do { __builtin_amdgcn_s_setprio(1); _Pragma("unroll") for (int m = 0; m < 4; ++m) _Pragma("unroll") for (int n = 0; n < 2; ++n) _Pragma("unroll") for (int k = 0; k < 2; ++k) \
;         acc[ai][bj][m][n] = __builtin_amdgcn_mfma_f32_16x16x32_bf16(Bt[n][k], At[m][k], acc[ai][bj][m][n], 0, 0, 0); __builtin_amdgcn_s_setprio(0); } while (0)
; #define PG8_WAIT_V(n) asm volatile("s_waitcnt vmcnt(" #n ")" ::: "memory")
; #define PG8_WAIT_L(n) asm volatile("s_waitcnt lgkmcnt(" #n ")" ::: "memory")
; #define PG8_BAR __builtin_amdgcn_s_barrier()
; #define PG8_SCHED __builtin_amdgcn_sched_barrier(0)
; template <class Epi, class Sched, bool ALIGN_EPI = false, bool SP2 = false>
; __device__ __forceinline__ void gemm_phase(PG8_LAS unsigned char* lds, const Gemm g, const Sched& S, const Epi& E) {
;     ...
;             PG8_LDB(B0, 0, 0); PG8_LDB(B1, 0, 1); PG8_SCHED; PG8_LDA(At, 0, 0); PG8_STAGE(PG8_SA(1, 1), a1 + hstep, voffA);
;             PG8_WAIT_V(8); PG8_WAIT_L(0); PG8_BAR; PG8_MMA(0, 0, At, B0); PG8_MMA(0, 1, At, B1); PG8_BAR; PG8_SCHED;
;             PG8_LDA(At, 0, 1); PG8_STAGE(PG8_SB(0, 0), b2, voffB); PG8_STAGE(PG8_SB(0, 1), b2 + hstep, voffB); PG8_STAGE(PG8_SA(0, 0), a2, voffA);
;             PG8_WAIT_V(8); PG8_WAIT_L(0); PG8_BAR; PG8_MMA(1, 0, At, B0); PG8_MMA(1, 1, At, B1); PG8_BAR; PG8_SCHED;
.LBB0_327:
	v_or_b32_e32 v68, 0x10000, v180
	v_add_u32_e32 v72, 0x10400, v180
	v_add_u32_e32 v76, 0x10800, v180
	v_add_u32_e32 v80, 0x10c00, v180
	v_or_b32_e32 v174, 0x14000, v180
	v_add_u32_e32 v181, 0x14400, v180
	ds_read_b128 v[68:71], v68
	ds_read_b128 v[72:75], v72
	ds_read_b128 v[76:79], v76
	ds_read_b128 v[80:83], v80
	ds_read_b128 v[174:177], v174
	ds_read_b128 v[182:185], v181
	v_add_u32_e32 v181, 0x14800, v180
	v_add_u32_e32 v190, 0x14c00, v180
	ds_read_b128 v[186:189], v181
	ds_read_b128 v[210:213], v190
	s_add_u32 s2, s0, 0xfffc0080
	s_addc_u32 s3, s1, -1
	s_cmp_eq_u32 s56, 12
	s_cselect_b32 s5, s27, s3
	s_cselect_b32 s4, s52, s2
	s_cselect_b32 s3, s25, s55
	s_cselect_b32 s2, s53, s54
	v_lshl_add_u64 v[190:191], s[0:1], 0, v[170:171]
	s_add_i32 m0, s29, 0xc000
	ds_read_b128 v[214:217], v179
	ds_read_b128 v[218:221], v179 offset:1024
	ds_read_b128 v[222:225], v179 offset:2048
	ds_read_b128 v[226:229], v179 offset:3072
	ds_read_b128 v[230:233], v179 offset:4096
	ds_read_b128 v[234:237], v179 offset:5120
	ds_read_b128 v[238:241], v179 offset:6144
	ds_read_b128 v[242:245], v179 offset:7168
	global_load_lds_dwordx4 v[190:191], off
	v_lshl_add_u64 v[190:191], s[0:1], 0, v[172:173]
	s_add_i32 m0, s29, 0xe000
	s_nop 0
	global_load_lds_dwordx4 v[190:191], off
	s_waitcnt vmcnt(8)
	s_waitcnt lgkmcnt(0)
	s_barrier
	s_setprio 1
	s_waitcnt lgkmcnt(0)
	v_mfma_f32_16x16x32_bf16 v[140:143], v[68:71], v[214:217], v[140:143]
	v_mfma_f32_16x16x32_bf16 v[136:139], v[76:79], v[214:217], v[136:139]
	v_mfma_f32_16x16x32_bf16 v[124:127], v[68:71], v[222:225], v[124:127]
	v_mfma_f32_16x16x32_bf16 v[120:123], v[76:79], v[222:225], v[120:123]
	v_mfma_f32_16x16x32_bf16 v[108:111], v[68:71], v[230:233], v[108:111]
	v_mfma_f32_16x16x32_bf16 v[104:107], v[76:79], v[230:233], v[104:107]
	v_mfma_f32_16x16x32_bf16 v[92:95], v[68:71], v[238:241], v[92:95]
	v_mfma_f32_16x16x32_bf16 v[88:91], v[76:79], v[238:241], v[88:91]
	v_mfma_f32_16x16x32_bf16 v[140:143], v[72:75], v[218:221], v[140:143]
	v_mfma_f32_16x16x32_bf16 v[136:139], v[80:83], v[218:221], v[136:139]
	v_mfma_f32_16x16x32_bf16 v[124:127], v[72:75], v[226:229], v[124:127]
	v_mfma_f32_16x16x32_bf16 v[120:123], v[80:83], v[226:229], v[120:123]
	v_mfma_f32_16x16x32_bf16 v[108:111], v[72:75], v[234:237], v[108:111]
	v_mfma_f32_16x16x32_bf16 v[104:107], v[80:83], v[234:237], v[104:107]
	v_mfma_f32_16x16x32_bf16 v[92:95], v[72:75], v[242:245], v[92:95]
	v_mfma_f32_16x16x32_bf16 v[88:91], v[80:83], v[242:245], v[88:91]
	s_setprio 0
	s_setprio 1
	v_mfma_f32_16x16x32_bf16 v[132:135], v[174:177], v[214:217], v[132:135]
	v_mfma_f32_16x16x32_bf16 v[128:131], v[186:189], v[214:217], v[128:131]
	v_mfma_f32_16x16x32_bf16 v[116:119], v[174:177], v[222:225], v[116:119]
	v_mfma_f32_16x16x32_bf16 v[112:115], v[186:189], v[222:225], v[112:115]
	v_mfma_f32_16x16x32_bf16 v[100:103], v[174:177], v[230:233], v[100:103]
	v_mfma_f32_16x16x32_bf16 v[96:99], v[186:189], v[230:233], v[96:99]
	v_mfma_f32_16x16x32_bf16 v[84:87], v[174:177], v[238:241], v[84:87]
	v_mfma_f32_16x16x32_bf16 v[64:67], v[186:189], v[238:241], v[64:67]
	v_mfma_f32_16x16x32_bf16 v[132:135], v[182:185], v[218:221], v[132:135]
	v_mfma_f32_16x16x32_bf16 v[128:131], v[210:213], v[218:221], v[128:131]
	v_mfma_f32_16x16x32_bf16 v[116:119], v[182:185], v[226:229], v[116:119]
	v_mfma_f32_16x16x32_bf16 v[112:115], v[210:213], v[226:229], v[112:115]
	s_setprio 0
	s_barrier
	v_mfma_f32_16x16x32_bf16 v[100:103], v[182:185], v[234:237], v[100:103]
	v_mfma_f32_16x16x32_bf16 v[96:99], v[210:213], v[234:237], v[96:99]
	v_mfma_f32_16x16x32_bf16 v[84:87], v[182:185], v[242:245], v[84:87]
	v_mfma_f32_16x16x32_bf16 v[64:67], v[210:213], v[242:245], v[64:67]
	s_mov_b32 m0, s30
	v_lshl_add_u64 v[190:191], s[2:3], 0, v[166:167]
	s_add_u32 s58, s2, 0x40000
	ds_read_b128 v[214:217], v179 offset:16384
	ds_read_b128 v[218:221], v179 offset:17408
	ds_read_b128 v[222:225], v179 offset:18432
	ds_read_b128 v[226:229], v179 offset:19456
	ds_read_b128 v[230:233], v179 offset:20480
	ds_read_b128 v[234:237], v179 offset:21504
	ds_read_b128 v[238:241], v179 offset:22528
	ds_read_b128 v[242:245], v179 offset:23552
	global_load_lds_dwordx4 v[190:191], off
	v_lshl_add_u64 v[208:209], s[2:3], 0, v[162:163]
	s_mov_b32 m0, s31
	s_addc_u32 s59, s3, 0
	global_load_lds_dwordx4 v[208:209], off
	v_lshl_add_u64 v[246:247], s[58:59], 0, v[166:167]
	s_mov_b32 m0, s33
	v_lshl_add_u64 v[248:249], s[4:5], 0, v[164:165]
	global_load_lds_dwordx4 v[246:247], off
	v_lshl_add_u64 v[246:247], s[58:59], 0, v[162:163]
	s_mov_b32 m0, s34
	s_nop 0
	global_load_lds_dwordx4 v[246:247], off
	v_lshl_add_u64 v[246:247], s[4:5], 0, v[168:169]
	s_mov_b32 m0, s29
	s_nop 0
	global_load_lds_dwordx4 v[246:247], off
	s_mov_b32 m0, s35
	s_nop 0
	global_load_lds_dwordx4 v[248:249], off
	s_waitcnt vmcnt(8)
	s_waitcnt lgkmcnt(0)
	s_barrier
; #define PG8_STAGE(bufoff, gbase, voff) do { _Pragma("unroll") for (int _i = 0; _i < 2; ++_i) \
;         __builtin_amdgcn_global_load_lds((const unsigned*)((const char*)(gbase) + (voff)[_i]), (PG8_LAS unsigned*)(lds + (bufoff) + ldsw + _i * 8192), 16, 0, 0); } while (0)
; #define PG8_LDA(dst, b, h) do { _Pragma("unroll") for (int m = 0; m < 4; ++m) _Pragma("unroll") for (int k = 0; k < 2; ++k) dst[m][k] = *(const PG8_LAS bf16x8*)(lds + PG8_SA(b, h) + aoff + m * 2048 + k * 1024); } while (0)
; #define PG8_LDB(dst, b, h) do { _Pragma("unroll") for (int n = 0; n < 2; ++n) _Pragma("unroll") for (int k = 0; k < 2; ++k) dst[n][k] = *(const PG8_LAS bf16x8*)(lds + PG8_SB(b, h) + boff + n * 2048 + k * 1024); } while (0)
; #define PG8_MMA(ai, bj, At, Bt) do { __builtin_amdgcn_s_setprio(1); _Pragma("unroll") for (int m = 0; m < 4; ++m) _Pragma("unroll") for (int n = 0; n < 2; ++n) _Pragma("unroll") for (int k = 0; k < 2; ++k) \
;         acc[ai][bj][m][n] = __builtin_amdgcn_mfma_f32_16x16x32_bf16(Bt[n][k], At[m][k], acc[ai][bj][m][n], 0, 0, 0); __builtin_amdgcn_s_setprio(0); } while (0)
; #define PG8_WAIT_V(n) asm volatile("s_waitcnt vmcnt(" #n ")" ::: "memory")
; #define PG8_WAIT_L(n) asm volatile("s_waitcnt lgkmcnt(" #n ")" ::: "memory")
; #define PG8_BAR __builtin_amdgcn_s_barrier()
; #define PG8_SCHED __builtin_amdgcn_sched_barrier(0)
; template <class Epi, class Sched, bool ALIGN_EPI = false, bool SP2 = false>
; __device__ __forceinline__ void gemm_phase(PG8_LAS unsigned char* lds, const Gemm g, const Sched& S, const Epi& E) {
;     ...
;             PG8_WAIT_V(8); PG8_WAIT_L(0); PG8_BAR; PG8_MMA(1, 0, At, B0); PG8_MMA(1, 1, At, B1); PG8_BAR; PG8_SCHED;
;             PG8_LDB(B0, 1, 0); PG8_LDB(B1, 1, 1); PG8_SCHED; PG8_LDA(At, 1, 0); PG8_STAGE(PG8_SA(0, 1), a2 + hstep, voffA);
;             PG8_WAIT_V(8); PG8_WAIT_L(0); PG8_BAR; PG8_MMA(0, 0, At, B0); PG8_MMA(0, 1, At, B1); PG8_BAR; PG8_SCHED;
	s_setprio 1
	s_waitcnt lgkmcnt(0)
	v_mfma_f32_16x16x32_bf16 v[60:63], v[68:71], v[214:217], v[60:63]
	v_mfma_f32_16x16x32_bf16 v[56:59], v[76:79], v[214:217], v[56:59]
	v_mfma_f32_16x16x32_bf16 v[44:47], v[68:71], v[222:225], v[44:47]
	v_mfma_f32_16x16x32_bf16 v[40:43], v[76:79], v[222:225], v[40:43]
	v_mfma_f32_16x16x32_bf16 v[28:31], v[68:71], v[230:233], v[28:31]
	v_mfma_f32_16x16x32_bf16 v[24:27], v[76:79], v[230:233], v[24:27]
	v_mfma_f32_16x16x32_bf16 v[12:15], v[68:71], v[238:241], v[12:15]
	v_mfma_f32_16x16x32_bf16 v[8:11], v[76:79], v[238:241], v[8:11]
	v_mfma_f32_16x16x32_bf16 v[60:63], v[72:75], v[218:221], v[60:63]
	v_mfma_f32_16x16x32_bf16 v[56:59], v[80:83], v[218:221], v[56:59]
	v_mfma_f32_16x16x32_bf16 v[44:47], v[72:75], v[226:229], v[44:47]
	v_mfma_f32_16x16x32_bf16 v[40:43], v[80:83], v[226:229], v[40:43]
	v_mfma_f32_16x16x32_bf16 v[28:31], v[72:75], v[234:237], v[28:31]
	v_mfma_f32_16x16x32_bf16 v[24:27], v[80:83], v[234:237], v[24:27]
	v_mfma_f32_16x16x32_bf16 v[12:15], v[72:75], v[242:245], v[12:15]
	v_mfma_f32_16x16x32_bf16 v[8:11], v[80:83], v[242:245], v[8:11]
	s_setprio 0
	s_setprio 1
	v_mfma_f32_16x16x32_bf16 v[52:55], v[174:177], v[214:217], v[52:55]
	v_mfma_f32_16x16x32_bf16 v[48:51], v[186:189], v[214:217], v[48:51]
	v_mfma_f32_16x16x32_bf16 v[36:39], v[174:177], v[222:225], v[36:39]
	v_mfma_f32_16x16x32_bf16 v[32:35], v[186:189], v[222:225], v[32:35]
	v_mfma_f32_16x16x32_bf16 v[20:23], v[174:177], v[230:233], v[20:23]
	v_mfma_f32_16x16x32_bf16 v[16:19], v[186:189], v[230:233], v[16:19]
	v_mfma_f32_16x16x32_bf16 v[4:7], v[174:177], v[238:241], v[4:7]
	v_mfma_f32_16x16x32_bf16 v[0:3], v[186:189], v[238:241], v[0:3]
	v_mfma_f32_16x16x32_bf16 v[52:55], v[182:185], v[218:221], v[52:55]
	v_mfma_f32_16x16x32_bf16 v[48:51], v[210:213], v[218:221], v[48:51]
	v_mfma_f32_16x16x32_bf16 v[36:39], v[182:185], v[226:229], v[36:39]
	v_mfma_f32_16x16x32_bf16 v[32:35], v[210:213], v[226:229], v[32:35]
	s_setprio 0
	s_barrier
	v_mfma_f32_16x16x32_bf16 v[20:23], v[182:185], v[234:237], v[20:23]
	v_mfma_f32_16x16x32_bf16 v[16:19], v[210:213], v[234:237], v[16:19]
	v_mfma_f32_16x16x32_bf16 v[4:7], v[182:185], v[242:245], v[4:7]
	v_mfma_f32_16x16x32_bf16 v[0:3], v[210:213], v[242:245], v[0:3]
	v_or_b32_e32 v68, 0x18000, v180
	v_add_u32_e32 v72, 0x18400, v180
	v_add_u32_e32 v76, 0x18800, v180
	v_add_u32_e32 v80, 0x18c00, v180
	v_or_b32_e32 v174, 0x1c000, v180
	v_add_u32_e32 v181, 0x1c400, v180
	ds_read_b128 v[68:71], v68
	ds_read_b128 v[72:75], v72
	ds_read_b128 v[76:79], v76
	ds_read_b128 v[80:83], v80
	ds_read_b128 v[174:177], v174
	ds_read_b128 v[182:185], v181
	v_add_u32_e32 v181, 0x1c800, v180
	v_add_u32_e32 v210, 0x1cc00, v180
	ds_read_b128 v[186:189], v181
	ds_read_b128 v[210:213], v210
	s_add_u32 s4, s4, 0x40000
	s_addc_u32 s5, s5, 0
	s_mov_b32 m0, s40
	v_lshl_add_u64 v[250:251], s[4:5], 0, v[168:169]
	ds_read_b128 v[214:217], v179 offset:32768
	ds_read_b128 v[218:221], v179 offset:33792
	ds_read_b128 v[222:225], v179 offset:34816
	ds_read_b128 v[226:229], v179 offset:35840
	ds_read_b128 v[230:233], v179 offset:36864
	ds_read_b128 v[234:237], v179 offset:37888
	ds_read_b128 v[238:241], v179 offset:38912
	ds_read_b128 v[242:245], v179 offset:39936
	global_load_lds_dwordx4 v[250:251], off
	v_lshl_add_u64 v[250:251], s[4:5], 0, v[164:165]
	s_mov_b32 m0, s41
	s_nop 0
	global_load_lds_dwordx4 v[250:251], off
	s_waitcnt vmcnt(8)
	s_waitcnt lgkmcnt(0)
	s_barrier
	s_setprio 1
	s_waitcnt lgkmcnt(0)
	v_mfma_f32_16x16x32_bf16 v[140:143], v[68:71], v[214:217], v[140:143]
	v_mfma_f32_16x16x32_bf16 v[136:139], v[76:79], v[214:217], v[136:139]
	v_mfma_f32_16x16x32_bf16 v[124:127], v[68:71], v[222:225], v[124:127]
	v_mfma_f32_16x16x32_bf16 v[120:123], v[76:79], v[222:225], v[120:123]
	v_mfma_f32_16x16x32_bf16 v[108:111], v[68:71], v[230:233], v[108:111]
	v_mfma_f32_16x16x32_bf16 v[104:107], v[76:79], v[230:233], v[104:107]
	v_mfma_f32_16x16x32_bf16 v[92:95], v[68:71], v[238:241], v[92:95]
	v_mfma_f32_16x16x32_bf16 v[88:91], v[76:79], v[238:241], v[88:91]
	v_mfma_f32_16x16x32_bf16 v[140:143], v[72:75], v[218:221], v[140:143]
	v_mfma_f32_16x16x32_bf16 v[136:139], v[80:83], v[218:221], v[136:139]
	v_mfma_f32_16x16x32_bf16 v[124:127], v[72:75], v[226:229], v[124:127]
	v_mfma_f32_16x16x32_bf16 v[120:123], v[80:83], v[226:229], v[120:123]
	v_mfma_f32_16x16x32_bf16 v[108:111], v[72:75], v[234:237], v[108:111]
	v_mfma_f32_16x16x32_bf16 v[104:107], v[80:83], v[234:237], v[104:107]
	v_mfma_f32_16x16x32_bf16 v[92:95], v[72:75], v[242:245], v[92:95]
	v_mfma_f32_16x16x32_bf16 v[88:91], v[80:83], v[242:245], v[88:91]
	s_setprio 0
	s_setprio 1
	v_mfma_f32_16x16x32_bf16 v[132:135], v[174:177], v[214:217], v[132:135]
	v_mfma_f32_16x16x32_bf16 v[128:131], v[186:189], v[214:217], v[128:131]
	v_mfma_f32_16x16x32_bf16 v[116:119], v[174:177], v[222:225], v[116:119]
	v_mfma_f32_16x16x32_bf16 v[112:115], v[186:189], v[222:225], v[112:115]
	v_mfma_f32_16x16x32_bf16 v[100:103], v[174:177], v[230:233], v[100:103]
	v_mfma_f32_16x16x32_bf16 v[96:99], v[186:189], v[230:233], v[96:99]
	v_mfma_f32_16x16x32_bf16 v[84:87], v[174:177], v[238:241], v[84:87]
	v_mfma_f32_16x16x32_bf16 v[64:67], v[186:189], v[238:241], v[64:67]
	v_mfma_f32_16x16x32_bf16 v[132:135], v[182:185], v[218:221], v[132:135]
	v_mfma_f32_16x16x32_bf16 v[128:131], v[210:213], v[218:221], v[128:131]
	v_mfma_f32_16x16x32_bf16 v[116:119], v[182:185], v[226:229], v[116:119]
	v_mfma_f32_16x16x32_bf16 v[112:115], v[210:213], v[226:229], v[112:115]
	s_setprio 0
	s_barrier
; #define PG8_STAGE(bufoff, gbase, voff) do { _Pragma("unroll") for (int _i = 0; _i < 2; ++_i) \
;         __builtin_amdgcn_global_load_lds((const unsigned*)((const char*)(gbase) + (voff)[_i]), (PG8_LAS unsigned*)(lds + (bufoff) + ldsw + _i * 8192), 16, 0, 0); } while (0)
; #define PG8_LDA(dst, b, h) do { _Pragma("unroll") for (int m = 0; m < 4; ++m) _Pragma("unroll") for (int k = 0; k < 2; ++k) dst[m][k] = *(const PG8_LAS bf16x8*)(lds + PG8_SA(b, h) + aoff + m * 2048 + k * 1024); } while (0)
; #define PG8_MMA(ai, bj, At, Bt) do { __builtin_amdgcn_s_setprio(1); _Pragma("unroll") for (int m = 0; m < 4; ++m) _Pragma("unroll") for (int n = 0; n < 2; ++n) _Pragma("unroll") for (int k = 0; k < 2; ++k) \
;         acc[ai][bj][m][n] = __builtin_amdgcn_mfma_f32_16x16x32_bf16(Bt[n][k], At[m][k], acc[ai][bj][m][n], 0, 0, 0); __builtin_amdgcn_s_setprio(0); } while (0)
; #define PG8_WAIT_V(n) asm volatile("s_waitcnt vmcnt(" #n ")" ::: "memory")
; #define PG8_WAIT_L(n) asm volatile("s_waitcnt lgkmcnt(" #n ")" ::: "memory")
; #define PG8_BAR __builtin_amdgcn_s_barrier()
; #define PG8_SCHED __builtin_amdgcn_sched_barrier(0)
; template <class Epi, class Sched, bool ALIGN_EPI = false, bool SP2 = false>
; __device__ __forceinline__ void gemm_phase(PG8_LAS unsigned char* lds, const Gemm g, const Sched& S, const Epi& E) {
;     ...
;             PG8_WAIT_V(8); PG8_WAIT_L(0); PG8_BAR; PG8_MMA(0, 0, At, B0); PG8_MMA(0, 1, At, B1); PG8_BAR; PG8_SCHED;
;             PG8_LDA(At, 1, 1); PG8_STAGE(PG8_SB(1, 0), b3, voffB); PG8_STAGE(PG8_SB(1, 1), b3 + hstep, voffB); PG8_STAGE(PG8_SA(1, 0), a3, voffA);
;             PG8_WAIT_V(8); PG8_WAIT_L(0); PG8_BAR; PG8_MMA(1, 0, At, B0); PG8_MMA(1, 1, At, B1); PG8_BAR; PG8_SCHED;
;     ...
;         if constexpr (ALIGN_EPI) { if (wr == 0) PG8_BAR; }
	v_mfma_f32_16x16x32_bf16 v[100:103], v[182:185], v[234:237], v[100:103]
	v_mfma_f32_16x16x32_bf16 v[96:99], v[210:213], v[234:237], v[96:99]
	v_mfma_f32_16x16x32_bf16 v[84:87], v[182:185], v[242:245], v[84:87]
	v_mfma_f32_16x16x32_bf16 v[64:67], v[210:213], v[242:245], v[64:67]
	s_mov_b32 m0, s45
	v_lshl_add_u64 v[190:191], v[190:191], 0, s[94:95]
	s_add_u32 s2, s2, 0x40080
	ds_read_b128 v[214:217], v179 offset:49152
	ds_read_b128 v[218:221], v179 offset:50176
	ds_read_b128 v[222:225], v179 offset:51200
	ds_read_b128 v[226:229], v179 offset:52224
	ds_read_b128 v[230:233], v179 offset:53248
	ds_read_b128 v[234:237], v179 offset:54272
	ds_read_b128 v[238:241], v179 offset:55296
	ds_read_b128 v[242:245], v179 offset:56320
	global_load_lds_dwordx4 v[190:191], off
	v_lshl_add_u64 v[190:191], v[208:209], 0, s[94:95]
	s_mov_b32 m0, s46
	s_addc_u32 s3, s3, 0
	global_load_lds_dwordx4 v[190:191], off
	v_lshl_add_u64 v[190:191], s[2:3], 0, v[166:167]
	s_mov_b32 m0, s49
	s_nop 0
	global_load_lds_dwordx4 v[190:191], off
	v_lshl_add_u64 v[190:191], s[2:3], 0, v[162:163]
	s_mov_b32 m0, s50
	s_nop 0
	global_load_lds_dwordx4 v[190:191], off
	v_lshl_add_u64 v[190:191], v[246:247], 0, s[94:95]
	s_mov_b32 m0, s47
	s_nop 0
	global_load_lds_dwordx4 v[190:191], off
	v_lshl_add_u64 v[190:191], v[248:249], 0, s[94:95]
	s_mov_b32 m0, s48
	s_nop 0
	global_load_lds_dwordx4 v[190:191], off
	s_waitcnt vmcnt(8)
	s_waitcnt lgkmcnt(0)
	s_barrier
	s_setprio 1
	s_waitcnt lgkmcnt(0)
	v_mfma_f32_16x16x32_bf16 v[60:63], v[68:71], v[214:217], v[60:63]
	v_mfma_f32_16x16x32_bf16 v[56:59], v[76:79], v[214:217], v[56:59]
	v_mfma_f32_16x16x32_bf16 v[44:47], v[68:71], v[222:225], v[44:47]
	v_mfma_f32_16x16x32_bf16 v[40:43], v[76:79], v[222:225], v[40:43]
	v_mfma_f32_16x16x32_bf16 v[28:31], v[68:71], v[230:233], v[28:31]
	v_mfma_f32_16x16x32_bf16 v[24:27], v[76:79], v[230:233], v[24:27]
	v_mfma_f32_16x16x32_bf16 v[12:15], v[68:71], v[238:241], v[12:15]
	v_mfma_f32_16x16x32_bf16 v[8:11], v[76:79], v[238:241], v[8:11]
	v_mfma_f32_16x16x32_bf16 v[60:63], v[72:75], v[218:221], v[60:63]
	v_mfma_f32_16x16x32_bf16 v[56:59], v[80:83], v[218:221], v[56:59]
	v_mfma_f32_16x16x32_bf16 v[44:47], v[72:75], v[226:229], v[44:47]
	v_mfma_f32_16x16x32_bf16 v[40:43], v[80:83], v[226:229], v[40:43]
	v_mfma_f32_16x16x32_bf16 v[28:31], v[72:75], v[234:237], v[28:31]
	v_mfma_f32_16x16x32_bf16 v[24:27], v[80:83], v[234:237], v[24:27]
	v_mfma_f32_16x16x32_bf16 v[12:15], v[72:75], v[242:245], v[12:15]
	v_mfma_f32_16x16x32_bf16 v[8:11], v[80:83], v[242:245], v[8:11]
	s_setprio 0
	s_setprio 1
	v_mfma_f32_16x16x32_bf16 v[52:55], v[174:177], v[214:217], v[52:55]
	v_mfma_f32_16x16x32_bf16 v[48:51], v[186:189], v[214:217], v[48:51]
	v_mfma_f32_16x16x32_bf16 v[36:39], v[174:177], v[222:225], v[36:39]
	v_mfma_f32_16x16x32_bf16 v[32:35], v[186:189], v[222:225], v[32:35]
	v_mfma_f32_16x16x32_bf16 v[20:23], v[174:177], v[230:233], v[20:23]
	v_mfma_f32_16x16x32_bf16 v[16:19], v[186:189], v[230:233], v[16:19]
	v_mfma_f32_16x16x32_bf16 v[4:7], v[174:177], v[238:241], v[4:7]
	v_mfma_f32_16x16x32_bf16 v[0:3], v[186:189], v[238:241], v[0:3]
	v_mfma_f32_16x16x32_bf16 v[52:55], v[182:185], v[218:221], v[52:55]
	v_mfma_f32_16x16x32_bf16 v[48:51], v[210:213], v[218:221], v[48:51]
	v_mfma_f32_16x16x32_bf16 v[36:39], v[182:185], v[226:229], v[36:39]
	v_mfma_f32_16x16x32_bf16 v[32:35], v[210:213], v[226:229], v[32:35]
	s_setprio 0
	s_barrier
	v_mfma_f32_16x16x32_bf16 v[20:23], v[182:185], v[234:237], v[20:23]
	v_mfma_f32_16x16x32_bf16 v[16:19], v[210:213], v[234:237], v[16:19]
	v_mfma_f32_16x16x32_bf16 v[4:7], v[182:185], v[242:245], v[4:7]
	v_mfma_f32_16x16x32_bf16 v[0:3], v[210:213], v[242:245], v[0:3]
	s_add_i32 s56, s56, 2
	s_add_u32 s0, s0, 0x100
	s_addc_u32 s1, s1, 0
	s_add_u32 s54, s54, 0x100
	s_addc_u32 s55, s55, 0
	s_cmp_gt_u32 s56, 13
	s_cbranch_scc0 .LBB0_327
	s_and_b64 vcc, exec, s[22:23]
	s_cbranch_vccz .LBB0_330
	s_barrier

; #define PG8_STAGE(bufoff, gbase, voff) do { _Pragma("unroll") for (int _i = 0; _i < 2; ++_i) \
;         __builtin_amdgcn_global_load_lds((const unsigned*)((const char*)(gbase) + (voff)[_i]), (PG8_LAS unsigned*)(lds + (bufoff) + ldsw + _i * 8192), 16, 0, 0); } while (0)
; #define PG8_LDA(dst, b, h) do { _Pragma("unroll") for (int m = 0; m < 4; ++m) _Pragma("unroll") for (int k = 0; k < 2; ++k) dst[m][k] = *(const PG8_LAS bf16x8*)(lds + PG8_SA(b, h) + aoff + m * 2048 + k * 1024); } while (0)
; #define PG8_LDB(dst, b, h) do { _Pragma("unroll") for (int n = 0; n < 2; ++n) _Pragma("unroll") for (int k = 0; k < 2; ++k) dst[n][k] = *(const PG8_LAS bf16x8*)(lds + PG8_SB(b, h) + boff + n * 2048 + k * 1024); } while (0)
; #define PG8_MMA(ai, bj, At, Bt) do { __builtin_amdgcn_s_setprio(1); _Pragma("unroll") for (int m = 0; m < 4; ++m) _Pragma("unroll") for (int n = 0; n < 2; ++n) _Pragma("unroll") for (int k = 0; k < 2; ++k) \
;         acc[ai][bj][m][n] = __builtin_amdgcn_mfma_f32_16x16x32_bf16(Bt[n][k], At[m][k], acc[ai][bj][m][n], 0, 0, 0); __builtin_amdgcn_s_setprio(0); } while (0)
; #define PG8_WAIT_V(n) asm volatile("s_waitcnt vmcnt(" #n ")" ::: "memory")
; #define PG8_WAIT_L(n) asm volatile("s_waitcnt lgkmcnt(" #n ")" ::: "memory")
; #define PG8_BAR __builtin_amdgcn_s_barrier()
; #define PG8_SCHED __builtin_amdgcn_sched_barrier(0)
; template <class Epi, class Sched, bool ALIGN_EPI = false, bool SP2 = false>
; __device__ __forceinline__ void gemm_phase(PG8_LAS unsigned char* lds, const Gemm g, const Sched& S, const Epi& E) {
;     ...
;             PG8_LDB(B0, 0, 0); PG8_LDB(B1, 0, 1); PG8_SCHED; PG8_LDA(At, 0, 0); PG8_STAGE(PG8_SA(1, 1), a1 + hstep, voffA);
;             PG8_WAIT_V(8); PG8_WAIT_L(0); PG8_BAR; PG8_MMA(0, 0, At, B0); PG8_MMA(0, 1, At, B1); PG8_BAR; PG8_SCHED;
;             PG8_LDA(At, 0, 1); PG8_STAGE(PG8_SB(0, 0), b2, voffB); PG8_STAGE(PG8_SB(0, 1), b2 + hstep, voffB); PG8_STAGE(PG8_SA(0, 0), a2, voffA);
;             PG8_WAIT_V(8); PG8_WAIT_L(0); PG8_BAR; PG8_MMA(1, 0, At, B0); PG8_MMA(1, 1, At, B1); PG8_BAR; PG8_SCHED;
.LBB0_446:
	v_or_b32_e32 v140, 0x10000, v166
	v_add_u32_e32 v162, 0x10400, v166
	ds_read_b128 v[140:143], v140
	ds_read_b128 v[168:171], v162
	v_add_u32_e32 v162, 0x10800, v166
	v_add_u32_e32 v163, 0x10c00, v166
	ds_read_b128 v[172:175], v162
	ds_read_b128 v[176:179], v163
	v_or_b32_e32 v162, 0x14000, v166
	v_add_u32_e32 v163, 0x14400, v166
	ds_read_b128 v[180:183], v162
	ds_read_b128 v[184:187], v163
	v_add_u32_e32 v162, 0x14800, v166
	v_add_u32_e32 v163, 0x14c00, v166
	ds_read_b128 v[188:191], v162
	ds_read_b128 v[210:213], v163
	s_add_u32 s16, s14, 0xfffc0080
	s_addc_u32 s17, s15, -1
	s_cmp_eq_u32 s53, 12
	s_cselect_b32 s19, s7, s17
	s_cselect_b32 s18, s49, s16
	s_cselect_b32 s17, s5, s52
	s_cselect_b32 s16, s50, s51
	s_mov_b32 m0, s43
	v_lshl_add_u64 v[162:163], s[14:15], 0, v[136:137]
	ds_read_b128 v[214:217], v165
	ds_read_b128 v[218:221], v165 offset:1024
	ds_read_b128 v[222:225], v165 offset:2048
	ds_read_b128 v[226:229], v165 offset:3072
	ds_read_b128 v[230:233], v165 offset:4096
	ds_read_b128 v[234:237], v165 offset:5120
	ds_read_b128 v[238:241], v165 offset:6144
	ds_read_b128 v[242:245], v165 offset:7168
	global_load_lds_dwordx4 v[162:163], off
	v_lshl_add_u64 v[162:163], s[14:15], 0, v[138:139]
	s_mov_b32 m0, s44
	s_nop 0
	global_load_lds_dwordx4 v[162:163], off
	s_waitcnt vmcnt(8)
	s_waitcnt lgkmcnt(0)
	s_barrier
	s_setprio 1
	s_waitcnt lgkmcnt(0)
	v_mfma_f32_16x16x32_bf16 v[124:127], v[140:143], v[214:217], v[124:127]
	v_mfma_f32_16x16x32_bf16 v[116:119], v[172:175], v[214:217], v[116:119]
	v_mfma_f32_16x16x32_bf16 v[108:111], v[140:143], v[222:225], v[108:111]
	v_mfma_f32_16x16x32_bf16 v[100:103], v[172:175], v[222:225], v[100:103]
	v_mfma_f32_16x16x32_bf16 v[92:95], v[140:143], v[230:233], v[92:95]
	v_mfma_f32_16x16x32_bf16 v[84:87], v[172:175], v[230:233], v[84:87]
	v_mfma_f32_16x16x32_bf16 v[76:79], v[140:143], v[238:241], v[76:79]
	v_mfma_f32_16x16x32_bf16 v[68:71], v[172:175], v[238:241], v[68:71]
	v_mfma_f32_16x16x32_bf16 v[124:127], v[168:171], v[218:221], v[124:127]
	v_mfma_f32_16x16x32_bf16 v[116:119], v[176:179], v[218:221], v[116:119]
	v_mfma_f32_16x16x32_bf16 v[108:111], v[168:171], v[226:229], v[108:111]
	v_mfma_f32_16x16x32_bf16 v[100:103], v[176:179], v[226:229], v[100:103]
	v_mfma_f32_16x16x32_bf16 v[92:95], v[168:171], v[234:237], v[92:95]
	v_mfma_f32_16x16x32_bf16 v[84:87], v[176:179], v[234:237], v[84:87]
	v_mfma_f32_16x16x32_bf16 v[76:79], v[168:171], v[242:245], v[76:79]
	v_mfma_f32_16x16x32_bf16 v[68:71], v[176:179], v[242:245], v[68:71]
	s_setprio 0
	s_setprio 1
	v_mfma_f32_16x16x32_bf16 v[120:123], v[180:183], v[214:217], v[120:123]
	v_mfma_f32_16x16x32_bf16 v[112:115], v[188:191], v[214:217], v[112:115]
	v_mfma_f32_16x16x32_bf16 v[104:107], v[180:183], v[222:225], v[104:107]
	v_mfma_f32_16x16x32_bf16 v[96:99], v[188:191], v[222:225], v[96:99]
	v_mfma_f32_16x16x32_bf16 v[88:91], v[180:183], v[230:233], v[88:91]
	v_mfma_f32_16x16x32_bf16 v[80:83], v[188:191], v[230:233], v[80:83]
	v_mfma_f32_16x16x32_bf16 v[72:75], v[180:183], v[238:241], v[72:75]
	v_mfma_f32_16x16x32_bf16 v[64:67], v[188:191], v[238:241], v[64:67]
	v_mfma_f32_16x16x32_bf16 v[120:123], v[184:187], v[218:221], v[120:123]
	v_mfma_f32_16x16x32_bf16 v[112:115], v[210:213], v[218:221], v[112:115]
	v_mfma_f32_16x16x32_bf16 v[104:107], v[184:187], v[226:229], v[104:107]
	v_mfma_f32_16x16x32_bf16 v[96:99], v[210:213], v[226:229], v[96:99]
	s_setprio 0
	s_barrier
	v_mfma_f32_16x16x32_bf16 v[88:91], v[184:187], v[234:237], v[88:91]
	v_mfma_f32_16x16x32_bf16 v[80:83], v[210:213], v[234:237], v[80:83]
	v_mfma_f32_16x16x32_bf16 v[72:75], v[184:187], v[242:245], v[72:75]
	v_mfma_f32_16x16x32_bf16 v[64:67], v[210:213], v[242:245], v[64:67]
	s_mov_b32 m0, s27
	v_lshl_add_u64 v[162:163], s[16:17], 0, v[132:133]
	s_add_u32 s54, s16, 0x40000
	ds_read_b128 v[214:217], v165 offset:16384
	ds_read_b128 v[218:221], v165 offset:17408
	ds_read_b128 v[222:225], v165 offset:18432
	ds_read_b128 v[226:229], v165 offset:19456
	ds_read_b128 v[230:233], v165 offset:20480
	ds_read_b128 v[234:237], v165 offset:21504
	ds_read_b128 v[238:241], v165 offset:22528
	ds_read_b128 v[242:245], v165 offset:23552
	global_load_lds_dwordx4 v[162:163], off
	v_lshl_add_u64 v[246:247], s[16:17], 0, v[128:129]
	s_mov_b32 m0, s28
	s_addc_u32 s55, s17, 0
	global_load_lds_dwordx4 v[246:247], off
	v_lshl_add_u64 v[248:249], s[54:55], 0, v[132:133]
	s_mov_b32 m0, s29
	v_lshl_add_u64 v[250:251], s[18:19], 0, v[130:131]
	global_load_lds_dwordx4 v[248:249], off
	v_lshl_add_u64 v[248:249], s[54:55], 0, v[128:129]
	s_mov_b32 m0, s30
	s_nop 0
	global_load_lds_dwordx4 v[248:249], off
	v_lshl_add_u64 v[248:249], s[18:19], 0, v[134:135]
	s_mov_b32 m0, s22
	s_nop 0
	global_load_lds_dwordx4 v[248:249], off
	s_mov_b32 m0, s31
	s_nop 0
	global_load_lds_dwordx4 v[250:251], off
	s_waitcnt vmcnt(8)
	s_waitcnt lgkmcnt(0)
	s_barrier
; #define PG8_STAGE(bufoff, gbase, voff) do { _Pragma("unroll") for (int _i = 0; _i < 2; ++_i) \
;         __builtin_amdgcn_global_load_lds((const unsigned*)((const char*)(gbase) + (voff)[_i]), (PG8_LAS unsigned*)(lds + (bufoff) + ldsw + _i * 8192), 16, 0, 0); } while (0)
; #define PG8_LDA(dst, b, h) do { _Pragma("unroll") for (int m = 0; m < 4; ++m) _Pragma("unroll") for (int k = 0; k < 2; ++k) dst[m][k] = *(const PG8_LAS bf16x8*)(lds + PG8_SA(b, h) + aoff + m * 2048 + k * 1024); } while (0)
; #define PG8_LDB(dst, b, h) do { _Pragma("unroll") for (int n = 0; n < 2; ++n) _Pragma("unroll") for (int k = 0; k < 2; ++k) dst[n][k] = *(const PG8_LAS bf16x8*)(lds + PG8_SB(b, h) + boff + n * 2048 + k * 1024); } while (0)
; #define PG8_MMA(ai, bj, At, Bt) do { __builtin_amdgcn_s_setprio(1); _Pragma("unroll") for (int m = 0; m < 4; ++m) _Pragma("unroll") for (int n = 0; n < 2; ++n) _Pragma("unroll") for (int k = 0; k < 2; ++k) \
;         acc[ai][bj][m][n] = __builtin_amdgcn_mfma_f32_16x16x32_bf16(Bt[n][k], At[m][k], acc[ai][bj][m][n], 0, 0, 0); __builtin_amdgcn_s_setprio(0); } while (0)
; #define PG8_WAIT_V(n) asm volatile("s_waitcnt vmcnt(" #n ")" ::: "memory")
; #define PG8_WAIT_L(n) asm volatile("s_waitcnt lgkmcnt(" #n ")" ::: "memory")
; #define PG8_BAR __builtin_amdgcn_s_barrier()
; #define PG8_SCHED __builtin_amdgcn_sched_barrier(0)
; template <class Epi, class Sched, bool ALIGN_EPI = false, bool SP2 = false>
; __device__ __forceinline__ void gemm_phase(PG8_LAS unsigned char* lds, const Gemm g, const Sched& S, const Epi& E) {
;     ...
;             PG8_WAIT_V(8); PG8_WAIT_L(0); PG8_BAR; PG8_MMA(1, 0, At, B0); PG8_MMA(1, 1, At, B1); PG8_BAR; PG8_SCHED;
;             PG8_LDB(B0, 1, 0); PG8_LDB(B1, 1, 1); PG8_SCHED; PG8_LDA(At, 1, 0); PG8_STAGE(PG8_SA(0, 1), a2 + hstep, voffA);
;             PG8_WAIT_V(8); PG8_WAIT_L(0); PG8_BAR; PG8_MMA(0, 0, At, B0); PG8_MMA(0, 1, At, B1); PG8_BAR; PG8_SCHED;
	s_setprio 1
	s_waitcnt lgkmcnt(0)
	v_mfma_f32_16x16x32_bf16 v[60:63], v[140:143], v[214:217], v[60:63]
	v_mfma_f32_16x16x32_bf16 v[52:55], v[172:175], v[214:217], v[52:55]
	v_mfma_f32_16x16x32_bf16 v[44:47], v[140:143], v[222:225], v[44:47]
	v_mfma_f32_16x16x32_bf16 v[36:39], v[172:175], v[222:225], v[36:39]
	v_mfma_f32_16x16x32_bf16 v[28:31], v[140:143], v[230:233], v[28:31]
	v_mfma_f32_16x16x32_bf16 v[20:23], v[172:175], v[230:233], v[20:23]
	v_mfma_f32_16x16x32_bf16 v[12:15], v[140:143], v[238:241], v[12:15]
	v_mfma_f32_16x16x32_bf16 v[4:7], v[172:175], v[238:241], v[4:7]
	v_mfma_f32_16x16x32_bf16 v[60:63], v[168:171], v[218:221], v[60:63]
	v_mfma_f32_16x16x32_bf16 v[52:55], v[176:179], v[218:221], v[52:55]
	v_mfma_f32_16x16x32_bf16 v[44:47], v[168:171], v[226:229], v[44:47]
	v_mfma_f32_16x16x32_bf16 v[36:39], v[176:179], v[226:229], v[36:39]
	v_mfma_f32_16x16x32_bf16 v[28:31], v[168:171], v[234:237], v[28:31]
	v_mfma_f32_16x16x32_bf16 v[20:23], v[176:179], v[234:237], v[20:23]
	v_mfma_f32_16x16x32_bf16 v[12:15], v[168:171], v[242:245], v[12:15]
	v_mfma_f32_16x16x32_bf16 v[4:7], v[176:179], v[242:245], v[4:7]
	s_setprio 0
	s_setprio 1
	v_mfma_f32_16x16x32_bf16 v[56:59], v[180:183], v[214:217], v[56:59]
	v_mfma_f32_16x16x32_bf16 v[48:51], v[188:191], v[214:217], v[48:51]
	v_mfma_f32_16x16x32_bf16 v[40:43], v[180:183], v[222:225], v[40:43]
	v_mfma_f32_16x16x32_bf16 v[32:35], v[188:191], v[222:225], v[32:35]
	v_mfma_f32_16x16x32_bf16 v[24:27], v[180:183], v[230:233], v[24:27]
	v_mfma_f32_16x16x32_bf16 v[16:19], v[188:191], v[230:233], v[16:19]
	v_mfma_f32_16x16x32_bf16 v[8:11], v[180:183], v[238:241], v[8:11]
	v_mfma_f32_16x16x32_bf16 v[0:3], v[188:191], v[238:241], v[0:3]
	v_mfma_f32_16x16x32_bf16 v[56:59], v[184:187], v[218:221], v[56:59]
	v_mfma_f32_16x16x32_bf16 v[48:51], v[210:213], v[218:221], v[48:51]
	v_mfma_f32_16x16x32_bf16 v[40:43], v[184:187], v[226:229], v[40:43]
	v_mfma_f32_16x16x32_bf16 v[32:35], v[210:213], v[226:229], v[32:35]
	s_setprio 0
	s_barrier
	v_mfma_f32_16x16x32_bf16 v[24:27], v[184:187], v[234:237], v[24:27]
	v_mfma_f32_16x16x32_bf16 v[16:19], v[210:213], v[234:237], v[16:19]
	v_mfma_f32_16x16x32_bf16 v[8:11], v[184:187], v[242:245], v[8:11]
	v_mfma_f32_16x16x32_bf16 v[0:3], v[210:213], v[242:245], v[0:3]
	v_or_b32_e32 v140, 0x18000, v166
	v_add_u32_e32 v167, 0x18400, v166
	ds_read_b128 v[140:143], v140
	ds_read_b128 v[168:171], v167
	v_add_u32_e32 v167, 0x18800, v166
	v_add_u32_e32 v176, 0x18c00, v166
	ds_read_b128 v[172:175], v167
	ds_read_b128 v[176:179], v176
	v_or_b32_e32 v167, 0x1c000, v166
	v_add_u32_e32 v184, 0x1c400, v166
	ds_read_b128 v[180:183], v167
	ds_read_b128 v[184:187], v184
	v_add_u32_e32 v167, 0x1c800, v166
	v_add_u32_e32 v208, 0x1cc00, v166
	ds_read_b128 v[188:191], v167
	ds_read_b128 v[210:213], v208
	s_add_u32 s18, s18, 0x40000
	s_addc_u32 s19, s19, 0
	s_mov_b32 m0, s33
	v_lshl_add_u64 v[208:209], s[18:19], 0, v[134:135]
	ds_read_b128 v[214:217], v165 offset:32768
	ds_read_b128 v[218:221], v165 offset:33792
	ds_read_b128 v[222:225], v165 offset:34816
	ds_read_b128 v[226:229], v165 offset:35840
	ds_read_b128 v[230:233], v165 offset:36864
	ds_read_b128 v[234:237], v165 offset:37888
	ds_read_b128 v[238:241], v165 offset:38912
	ds_read_b128 v[242:245], v165 offset:39936
	global_load_lds_dwordx4 v[208:209], off
	v_lshl_add_u64 v[208:209], s[18:19], 0, v[130:131]
	s_mov_b32 m0, s34
	s_nop 0
	global_load_lds_dwordx4 v[208:209], off
	s_waitcnt vmcnt(8)
	s_waitcnt lgkmcnt(0)
	s_barrier
	s_setprio 1
	s_waitcnt lgkmcnt(0)
	v_mfma_f32_16x16x32_bf16 v[124:127], v[140:143], v[214:217], v[124:127]
	v_mfma_f32_16x16x32_bf16 v[116:119], v[172:175], v[214:217], v[116:119]
	v_mfma_f32_16x16x32_bf16 v[108:111], v[140:143], v[222:225], v[108:111]
	v_mfma_f32_16x16x32_bf16 v[100:103], v[172:175], v[222:225], v[100:103]
	v_mfma_f32_16x16x32_bf16 v[92:95], v[140:143], v[230:233], v[92:95]
	v_mfma_f32_16x16x32_bf16 v[84:87], v[172:175], v[230:233], v[84:87]
	v_mfma_f32_16x16x32_bf16 v[76:79], v[140:143], v[238:241], v[76:79]
	v_mfma_f32_16x16x32_bf16 v[68:71], v[172:175], v[238:241], v[68:71]
	v_mfma_f32_16x16x32_bf16 v[124:127], v[168:171], v[218:221], v[124:127]
	v_mfma_f32_16x16x32_bf16 v[116:119], v[176:179], v[218:221], v[116:119]
	v_mfma_f32_16x16x32_bf16 v[108:111], v[168:171], v[226:229], v[108:111]
	v_mfma_f32_16x16x32_bf16 v[100:103], v[176:179], v[226:229], v[100:103]
	v_mfma_f32_16x16x32_bf16 v[92:95], v[168:171], v[234:237], v[92:95]
	v_mfma_f32_16x16x32_bf16 v[84:87], v[176:179], v[234:237], v[84:87]
	v_mfma_f32_16x16x32_bf16 v[76:79], v[168:171], v[242:245], v[76:79]
	v_mfma_f32_16x16x32_bf16 v[68:71], v[176:179], v[242:245], v[68:71]
	s_setprio 0
	s_setprio 1
	v_mfma_f32_16x16x32_bf16 v[120:123], v[180:183], v[214:217], v[120:123]
	v_mfma_f32_16x16x32_bf16 v[112:115], v[188:191], v[214:217], v[112:115]
	v_mfma_f32_16x16x32_bf16 v[104:107], v[180:183], v[222:225], v[104:107]
	v_mfma_f32_16x16x32_bf16 v[96:99], v[188:191], v[222:225], v[96:99]
	v_mfma_f32_16x16x32_bf16 v[88:91], v[180:183], v[230:233], v[88:91]
	v_mfma_f32_16x16x32_bf16 v[80:83], v[188:191], v[230:233], v[80:83]
	v_mfma_f32_16x16x32_bf16 v[72:75], v[180:183], v[238:241], v[72:75]
	v_mfma_f32_16x16x32_bf16 v[64:67], v[188:191], v[238:241], v[64:67]
	v_mfma_f32_16x16x32_bf16 v[120:123], v[184:187], v[218:221], v[120:123]
	v_mfma_f32_16x16x32_bf16 v[112:115], v[210:213], v[218:221], v[112:115]
	v_mfma_f32_16x16x32_bf16 v[104:107], v[184:187], v[226:229], v[104:107]
	v_mfma_f32_16x16x32_bf16 v[96:99], v[210:213], v[226:229], v[96:99]
	s_setprio 0
	s_barrier
; #define PG8_STAGE(bufoff, gbase, voff) do { _Pragma("unroll") for (int _i = 0; _i < 2; ++_i) \
;         __builtin_amdgcn_global_load_lds((const unsigned*)((const char*)(gbase) + (voff)[_i]), (PG8_LAS unsigned*)(lds + (bufoff) + ldsw + _i * 8192), 16, 0, 0); } while (0)
; #define PG8_LDA(dst, b, h) do { _Pragma("unroll") for (int m = 0; m < 4; ++m) _Pragma("unroll") for (int k = 0; k < 2; ++k) dst[m][k] = *(const PG8_LAS bf16x8*)(lds + PG8_SA(b, h) + aoff + m * 2048 + k * 1024); } while (0)
; #define PG8_MMA(ai, bj, At, Bt) do { __builtin_amdgcn_s_setprio(1); _Pragma("unroll") for (int m = 0; m < 4; ++m) _Pragma("unroll") for (int n = 0; n < 2; ++n) _Pragma("unroll") for (int k = 0; k < 2; ++k) \
;         acc[ai][bj][m][n] = __builtin_amdgcn_mfma_f32_16x16x32_bf16(Bt[n][k], At[m][k], acc[ai][bj][m][n], 0, 0, 0); __builtin_amdgcn_s_setprio(0); } while (0)
; #define PG8_WAIT_V(n) asm volatile("s_waitcnt vmcnt(" #n ")" ::: "memory")
; #define PG8_WAIT_L(n) asm volatile("s_waitcnt lgkmcnt(" #n ")" ::: "memory")
; #define PG8_BAR __builtin_amdgcn_s_barrier()
; #define PG8_SCHED __builtin_amdgcn_sched_barrier(0)
; template <class Epi, class Sched, bool ALIGN_EPI = false, bool SP2 = false>
; __device__ __forceinline__ void gemm_phase(PG8_LAS unsigned char* lds, const Gemm g, const Sched& S, const Epi& E) {
;     ...
;             PG8_WAIT_V(8); PG8_WAIT_L(0); PG8_BAR; PG8_MMA(0, 0, At, B0); PG8_MMA(0, 1, At, B1); PG8_BAR; PG8_SCHED;
;             PG8_LDA(At, 1, 1); PG8_STAGE(PG8_SB(1, 0), b3, voffB); PG8_STAGE(PG8_SB(1, 1), b3 + hstep, voffB); PG8_STAGE(PG8_SA(1, 0), a3, voffA);
;             PG8_WAIT_V(8); PG8_WAIT_L(0); PG8_BAR; PG8_MMA(1, 0, At, B0); PG8_MMA(1, 1, At, B1); PG8_BAR; PG8_SCHED;
;     ...
;         if constexpr (ALIGN_EPI) { if (wr == 0) PG8_BAR; }
	v_mfma_f32_16x16x32_bf16 v[88:91], v[184:187], v[234:237], v[88:91]
	v_mfma_f32_16x16x32_bf16 v[80:83], v[210:213], v[234:237], v[80:83]
	v_mfma_f32_16x16x32_bf16 v[72:75], v[184:187], v[242:245], v[72:75]
	v_mfma_f32_16x16x32_bf16 v[64:67], v[210:213], v[242:245], v[64:67]
	s_mov_b32 m0, s37
	v_lshl_add_u64 v[162:163], v[162:163], 0, s[94:95]
	s_add_u32 s16, s16, 0x40080
	ds_read_b128 v[214:217], v165 offset:49152
	ds_read_b128 v[218:221], v165 offset:50176
	ds_read_b128 v[222:225], v165 offset:51200
	ds_read_b128 v[226:229], v165 offset:52224
	ds_read_b128 v[230:233], v165 offset:53248
	ds_read_b128 v[234:237], v165 offset:54272
	ds_read_b128 v[238:241], v165 offset:55296
	ds_read_b128 v[242:245], v165 offset:56320
	global_load_lds_dwordx4 v[162:163], off
	v_lshl_add_u64 v[162:163], v[246:247], 0, s[94:95]
	s_mov_b32 m0, s38
	s_addc_u32 s17, s17, 0
	global_load_lds_dwordx4 v[162:163], off
	v_lshl_add_u64 v[162:163], s[16:17], 0, v[132:133]
	s_mov_b32 m0, s41
	s_nop 0
	global_load_lds_dwordx4 v[162:163], off
	v_lshl_add_u64 v[162:163], s[16:17], 0, v[128:129]
	s_mov_b32 m0, s42
	s_nop 0
	global_load_lds_dwordx4 v[162:163], off
	v_lshl_add_u64 v[162:163], v[248:249], 0, s[94:95]
	s_mov_b32 m0, s39
	s_nop 0
	global_load_lds_dwordx4 v[162:163], off
	v_lshl_add_u64 v[162:163], v[250:251], 0, s[94:95]
	s_mov_b32 m0, s40
	s_nop 0
	global_load_lds_dwordx4 v[162:163], off
	s_waitcnt vmcnt(8)
	s_waitcnt lgkmcnt(0)
	s_barrier
	s_setprio 1
	s_waitcnt lgkmcnt(0)
	v_mfma_f32_16x16x32_bf16 v[60:63], v[140:143], v[214:217], v[60:63]
	v_mfma_f32_16x16x32_bf16 v[52:55], v[172:175], v[214:217], v[52:55]
	v_mfma_f32_16x16x32_bf16 v[44:47], v[140:143], v[222:225], v[44:47]
	v_mfma_f32_16x16x32_bf16 v[36:39], v[172:175], v[222:225], v[36:39]
	v_mfma_f32_16x16x32_bf16 v[28:31], v[140:143], v[230:233], v[28:31]
	v_mfma_f32_16x16x32_bf16 v[20:23], v[172:175], v[230:233], v[20:23]
	v_mfma_f32_16x16x32_bf16 v[12:15], v[140:143], v[238:241], v[12:15]
	v_mfma_f32_16x16x32_bf16 v[4:7], v[172:175], v[238:241], v[4:7]
	v_mfma_f32_16x16x32_bf16 v[60:63], v[168:171], v[218:221], v[60:63]
	v_mfma_f32_16x16x32_bf16 v[52:55], v[176:179], v[218:221], v[52:55]
	v_mfma_f32_16x16x32_bf16 v[44:47], v[168:171], v[226:229], v[44:47]
	v_mfma_f32_16x16x32_bf16 v[36:39], v[176:179], v[226:229], v[36:39]
	v_mfma_f32_16x16x32_bf16 v[28:31], v[168:171], v[234:237], v[28:31]
	v_mfma_f32_16x16x32_bf16 v[20:23], v[176:179], v[234:237], v[20:23]
	v_mfma_f32_16x16x32_bf16 v[12:15], v[168:171], v[242:245], v[12:15]
	v_mfma_f32_16x16x32_bf16 v[4:7], v[176:179], v[242:245], v[4:7]
	s_setprio 0
	s_setprio 1
	v_mfma_f32_16x16x32_bf16 v[56:59], v[180:183], v[214:217], v[56:59]
	v_mfma_f32_16x16x32_bf16 v[48:51], v[188:191], v[214:217], v[48:51]
	v_mfma_f32_16x16x32_bf16 v[40:43], v[180:183], v[222:225], v[40:43]
	v_mfma_f32_16x16x32_bf16 v[32:35], v[188:191], v[222:225], v[32:35]
	v_mfma_f32_16x16x32_bf16 v[24:27], v[180:183], v[230:233], v[24:27]
	v_mfma_f32_16x16x32_bf16 v[16:19], v[188:191], v[230:233], v[16:19]
	v_mfma_f32_16x16x32_bf16 v[8:11], v[180:183], v[238:241], v[8:11]
	v_mfma_f32_16x16x32_bf16 v[0:3], v[188:191], v[238:241], v[0:3]
	v_mfma_f32_16x16x32_bf16 v[56:59], v[184:187], v[218:221], v[56:59]
	v_mfma_f32_16x16x32_bf16 v[48:51], v[210:213], v[218:221], v[48:51]
	v_mfma_f32_16x16x32_bf16 v[40:43], v[184:187], v[226:229], v[40:43]
	v_mfma_f32_16x16x32_bf16 v[32:35], v[210:213], v[226:229], v[32:35]
	s_setprio 0
	s_barrier
	v_mfma_f32_16x16x32_bf16 v[24:27], v[184:187], v[234:237], v[24:27]
	v_mfma_f32_16x16x32_bf16 v[16:19], v[210:213], v[234:237], v[16:19]
	v_mfma_f32_16x16x32_bf16 v[8:11], v[184:187], v[242:245], v[8:11]
	v_mfma_f32_16x16x32_bf16 v[0:3], v[210:213], v[242:245], v[0:3]
	s_add_i32 s53, s53, 2
	s_add_u32 s14, s14, 0x100
	s_addc_u32 s15, s15, 0
	s_add_u32 s51, s51, 0x100
	s_addc_u32 s52, s52, 0
	s_cmp_gt_u32 s53, 13
	s_cbranch_scc0 .LBB0_446
	s_and_b64 vcc, exec, s[2:3]
	s_cbranch_vccz .LBB0_449
	s_barrier

; #define PG8_STAGE(bufoff, gbase, voff) do { _Pragma("unroll") for (int _i = 0; _i < 2; ++_i) \
;         __builtin_amdgcn_global_load_lds((const unsigned*)((const char*)(gbase) + (voff)[_i]), (PG8_LAS unsigned*)(lds + (bufoff) + ldsw + _i * 8192), 16, 0, 0); } while (0)
; #define PG8_LDA(dst, b, h) do { _Pragma("unroll") for (int m = 0; m < 4; ++m) _Pragma("unroll") for (int k = 0; k < 2; ++k) dst[m][k] = *(const PG8_LAS bf16x8*)(lds + PG8_SA(b, h) + aoff + m * 2048 + k * 1024); } while (0)
; #define PG8_LDB(dst, b, h) do { _Pragma("unroll") for (int n = 0; n < 2; ++n) _Pragma("unroll") for (int k = 0; k < 2; ++k) dst[n][k] = *(const PG8_LAS bf16x8*)(lds + PG8_SB(b, h) + boff + n * 2048 + k * 1024); } while (0)
; #define PG8_MMA(ai, bj, At, Bt) do { __builtin_amdgcn_s_setprio(1); _Pragma("unroll") for (int m = 0; m < 4; ++m) _Pragma("unroll") for (int n = 0; n < 2; ++n) _Pragma("unroll") for (int k = 0; k < 2; ++k) \
;         acc[ai][bj][m][n] = __builtin_amdgcn_mfma_f32_16x16x32_bf16(Bt[n][k], At[m][k], acc[ai][bj][m][n], 0, 0, 0); __builtin_amdgcn_s_setprio(0); } while (0)
; #define PG8_WAIT_V(n) asm volatile("s_waitcnt vmcnt(" #n ")" ::: "memory")
; #define PG8_WAIT_L(n) asm volatile("s_waitcnt lgkmcnt(" #n ")" ::: "memory")
; #define PG8_BAR __builtin_amdgcn_s_barrier()
; #define PG8_SCHED __builtin_amdgcn_sched_barrier(0)
; template <class Epi, class Sched, bool ALIGN_EPI = false, bool SP2 = false>
; __device__ __forceinline__ void gemm_phase(PG8_LAS unsigned char* lds, const Gemm g, const Sched& S, const Epi& E) {
;     ...
;             PG8_LDB(B0, 0, 0); PG8_LDB(B1, 0, 1); PG8_SCHED; PG8_LDA(At, 0, 0); PG8_STAGE(PG8_SA(1, 1), a1 + hstep, voffA);
;             PG8_WAIT_V(8); PG8_WAIT_L(0); PG8_BAR; PG8_MMA(0, 0, At, B0); PG8_MMA(0, 1, At, B1); PG8_BAR; PG8_SCHED;
;             PG8_LDA(At, 0, 1); PG8_STAGE(PG8_SB(0, 0), b2, voffB); PG8_STAGE(PG8_SB(0, 1), b2 + hstep, voffB); PG8_STAGE(PG8_SA(0, 0), a2, voffA);
;             PG8_WAIT_V(8); PG8_WAIT_L(0); PG8_BAR; PG8_MMA(1, 0, At, B0); PG8_MMA(1, 1, At, B1); PG8_BAR; PG8_SCHED;
.LBB0_545:
	v_or_b32_e32 v128, 0x10000, v182
	v_add_u32_e32 v132, 0x10400, v182
	v_add_u32_e32 v136, 0x10800, v182
	v_add_u32_e32 v140, 0x10c00, v182
	v_or_b32_e32 v174, 0x14000, v182
	v_add_u32_e32 v178, 0x14400, v182
	ds_read_b128 v[128:131], v128
	ds_read_b128 v[132:135], v132
	ds_read_b128 v[136:139], v136
	ds_read_b128 v[140:143], v140
	ds_read_b128 v[174:177], v174
	ds_read_b128 v[184:187], v178
	v_add_u32_e32 v178, 0x14800, v182
	v_add_u32_e32 v179, 0x14c00, v182
	ds_read_b128 v[188:191], v178
	ds_read_b128 v[210:213], v179
	s_add_u32 s2, s0, 0x100
	s_addc_u32 s3, s1, 0
	s_cmp_eq_u32 s13, 40
	s_cselect_b32 s7, s27, s3
	s_cselect_b32 s6, s26, s2
	s_cselect_b32 s5, s37, s11
	s_cselect_b32 s4, s36, s10
	v_lshl_add_u64 v[178:179], s[0:1], 0, v[170:171]
	s_add_i32 m0, s29, 0xc000
	ds_read_b128 v[214:217], v181
	ds_read_b128 v[218:221], v181 offset:1024
	ds_read_b128 v[222:225], v181 offset:2048
	ds_read_b128 v[226:229], v181 offset:3072
	ds_read_b128 v[230:233], v181 offset:4096
	ds_read_b128 v[234:237], v181 offset:5120
	ds_read_b128 v[238:241], v181 offset:6144
	ds_read_b128 v[242:245], v181 offset:7168
	global_load_lds_dwordx4 v[178:179], off
	v_lshl_add_u64 v[178:179], s[0:1], 0, v[172:173]
	s_add_i32 m0, s29, 0xe000
	s_nop 0
	global_load_lds_dwordx4 v[178:179], off
	s_waitcnt vmcnt(8)
	s_waitcnt lgkmcnt(0)
	s_barrier
	s_setprio 1
	s_waitcnt lgkmcnt(0)
	v_mfma_f32_16x16x32_bf16 v[124:127], v[128:131], v[214:217], v[124:127]
	v_mfma_f32_16x16x32_bf16 v[120:123], v[136:139], v[214:217], v[120:123]
	v_mfma_f32_16x16x32_bf16 v[108:111], v[128:131], v[222:225], v[108:111]
	v_mfma_f32_16x16x32_bf16 v[104:107], v[136:139], v[222:225], v[104:107]
	v_mfma_f32_16x16x32_bf16 v[92:95], v[128:131], v[230:233], v[92:95]
	v_mfma_f32_16x16x32_bf16 v[88:91], v[136:139], v[230:233], v[88:91]
	v_mfma_f32_16x16x32_bf16 v[76:79], v[128:131], v[238:241], v[76:79]
	v_mfma_f32_16x16x32_bf16 v[72:75], v[136:139], v[238:241], v[72:75]
	v_mfma_f32_16x16x32_bf16 v[124:127], v[132:135], v[218:221], v[124:127]
	v_mfma_f32_16x16x32_bf16 v[120:123], v[140:143], v[218:221], v[120:123]
	v_mfma_f32_16x16x32_bf16 v[108:111], v[132:135], v[226:229], v[108:111]
	v_mfma_f32_16x16x32_bf16 v[104:107], v[140:143], v[226:229], v[104:107]
	v_mfma_f32_16x16x32_bf16 v[92:95], v[132:135], v[234:237], v[92:95]
	v_mfma_f32_16x16x32_bf16 v[88:91], v[140:143], v[234:237], v[88:91]
	v_mfma_f32_16x16x32_bf16 v[76:79], v[132:135], v[242:245], v[76:79]
	v_mfma_f32_16x16x32_bf16 v[72:75], v[140:143], v[242:245], v[72:75]
	s_setprio 0
	s_setprio 1
	v_mfma_f32_16x16x32_bf16 v[116:119], v[174:177], v[214:217], v[116:119]
	v_mfma_f32_16x16x32_bf16 v[112:115], v[188:191], v[214:217], v[112:115]
	v_mfma_f32_16x16x32_bf16 v[100:103], v[174:177], v[222:225], v[100:103]
	v_mfma_f32_16x16x32_bf16 v[96:99], v[188:191], v[222:225], v[96:99]
	v_mfma_f32_16x16x32_bf16 v[84:87], v[174:177], v[230:233], v[84:87]
	v_mfma_f32_16x16x32_bf16 v[80:83], v[188:191], v[230:233], v[80:83]
	v_mfma_f32_16x16x32_bf16 v[68:71], v[174:177], v[238:241], v[68:71]
	v_mfma_f32_16x16x32_bf16 v[64:67], v[188:191], v[238:241], v[64:67]
	v_mfma_f32_16x16x32_bf16 v[116:119], v[184:187], v[218:221], v[116:119]
	v_mfma_f32_16x16x32_bf16 v[112:115], v[210:213], v[218:221], v[112:115]
	v_mfma_f32_16x16x32_bf16 v[100:103], v[184:187], v[226:229], v[100:103]
	v_mfma_f32_16x16x32_bf16 v[96:99], v[210:213], v[226:229], v[96:99]
	s_setprio 0
	s_barrier
	v_mfma_f32_16x16x32_bf16 v[84:87], v[184:187], v[234:237], v[84:87]
	v_mfma_f32_16x16x32_bf16 v[80:83], v[210:213], v[234:237], v[80:83]
	v_mfma_f32_16x16x32_bf16 v[68:71], v[184:187], v[242:245], v[68:71]
	v_mfma_f32_16x16x32_bf16 v[64:67], v[210:213], v[242:245], v[64:67]
	s_mov_b32 m0, s35
	v_lshl_add_u64 v[178:179], s[4:5], 0, v[166:167]
	s_add_u32 s0, s4, 0xb0000
	ds_read_b128 v[214:217], v181 offset:16384
	ds_read_b128 v[218:221], v181 offset:17408
	ds_read_b128 v[222:225], v181 offset:18432
	ds_read_b128 v[226:229], v181 offset:19456
	ds_read_b128 v[230:233], v181 offset:20480
	ds_read_b128 v[234:237], v181 offset:21504
	ds_read_b128 v[238:241], v181 offset:22528
	ds_read_b128 v[242:245], v181 offset:23552
	global_load_lds_dwordx4 v[178:179], off
	v_lshl_add_u64 v[208:209], s[4:5], 0, v[162:163]
	s_mov_b32 m0, s38
	s_addc_u32 s1, s5, 0
	global_load_lds_dwordx4 v[208:209], off
	v_lshl_add_u64 v[246:247], s[0:1], 0, v[166:167]
	s_mov_b32 m0, s39
	v_lshl_add_u64 v[248:249], s[6:7], 0, v[164:165]
	global_load_lds_dwordx4 v[246:247], off
	v_lshl_add_u64 v[246:247], s[0:1], 0, v[162:163]
	s_mov_b32 m0, s40
	s_nop 0
	global_load_lds_dwordx4 v[246:247], off
	v_lshl_add_u64 v[246:247], s[6:7], 0, v[168:169]
	s_mov_b32 m0, s29
	s_nop 0
	global_load_lds_dwordx4 v[246:247], off
	s_mov_b32 m0, s41
	s_nop 0
	global_load_lds_dwordx4 v[248:249], off
	s_waitcnt vmcnt(8)
	s_waitcnt lgkmcnt(0)
	s_barrier
; #define PG8_STAGE(bufoff, gbase, voff) do { _Pragma("unroll") for (int _i = 0; _i < 2; ++_i) \
;         __builtin_amdgcn_global_load_lds((const unsigned*)((const char*)(gbase) + (voff)[_i]), (PG8_LAS unsigned*)(lds + (bufoff) + ldsw + _i * 8192), 16, 0, 0); } while (0)
; #define PG8_LDA(dst, b, h) do { _Pragma("unroll") for (int m = 0; m < 4; ++m) _Pragma("unroll") for (int k = 0; k < 2; ++k) dst[m][k] = *(const PG8_LAS bf16x8*)(lds + PG8_SA(b, h) + aoff + m * 2048 + k * 1024); } while (0)
; #define PG8_LDB(dst, b, h) do { _Pragma("unroll") for (int n = 0; n < 2; ++n) _Pragma("unroll") for (int k = 0; k < 2; ++k) dst[n][k] = *(const PG8_LAS bf16x8*)(lds + PG8_SB(b, h) + boff + n * 2048 + k * 1024); } while (0)
; #define PG8_MMA(ai, bj, At, Bt) do { __builtin_amdgcn_s_setprio(1); _Pragma("unroll") for (int m = 0; m < 4; ++m) _Pragma("unroll") for (int n = 0; n < 2; ++n) _Pragma("unroll") for (int k = 0; k < 2; ++k) \
;         acc[ai][bj][m][n] = __builtin_amdgcn_mfma_f32_16x16x32_bf16(Bt[n][k], At[m][k], acc[ai][bj][m][n], 0, 0, 0); __builtin_amdgcn_s_setprio(0); } while (0)
; #define PG8_WAIT_V(n) asm volatile("s_waitcnt vmcnt(" #n ")" ::: "memory")
; #define PG8_WAIT_L(n) asm volatile("s_waitcnt lgkmcnt(" #n ")" ::: "memory")
; #define PG8_BAR __builtin_amdgcn_s_barrier()
; #define PG8_SCHED __builtin_amdgcn_sched_barrier(0)
; template <class Epi, class Sched, bool ALIGN_EPI = false, bool SP2 = false>
; __device__ __forceinline__ void gemm_phase(PG8_LAS unsigned char* lds, const Gemm g, const Sched& S, const Epi& E) {
;     ...
;             PG8_WAIT_V(8); PG8_WAIT_L(0); PG8_BAR; PG8_MMA(1, 0, At, B0); PG8_MMA(1, 1, At, B1); PG8_BAR; PG8_SCHED;
;             PG8_LDB(B0, 1, 0); PG8_LDB(B1, 1, 1); PG8_SCHED; PG8_LDA(At, 1, 0); PG8_STAGE(PG8_SA(0, 1), a2 + hstep, voffA);
;             PG8_WAIT_V(8); PG8_WAIT_L(0); PG8_BAR; PG8_MMA(0, 0, At, B0); PG8_MMA(0, 1, At, B1); PG8_BAR; PG8_SCHED;
	s_setprio 1
	s_waitcnt lgkmcnt(0)
	v_mfma_f32_16x16x32_bf16 v[60:63], v[128:131], v[214:217], v[60:63]
	v_mfma_f32_16x16x32_bf16 v[56:59], v[136:139], v[214:217], v[56:59]
	v_mfma_f32_16x16x32_bf16 v[44:47], v[128:131], v[222:225], v[44:47]
	v_mfma_f32_16x16x32_bf16 v[40:43], v[136:139], v[222:225], v[40:43]
	v_mfma_f32_16x16x32_bf16 v[28:31], v[128:131], v[230:233], v[28:31]
	v_mfma_f32_16x16x32_bf16 v[24:27], v[136:139], v[230:233], v[24:27]
	v_mfma_f32_16x16x32_bf16 v[12:15], v[128:131], v[238:241], v[12:15]
	v_mfma_f32_16x16x32_bf16 v[8:11], v[136:139], v[238:241], v[8:11]
	v_mfma_f32_16x16x32_bf16 v[60:63], v[132:135], v[218:221], v[60:63]
	v_mfma_f32_16x16x32_bf16 v[56:59], v[140:143], v[218:221], v[56:59]
	v_mfma_f32_16x16x32_bf16 v[44:47], v[132:135], v[226:229], v[44:47]
	v_mfma_f32_16x16x32_bf16 v[40:43], v[140:143], v[226:229], v[40:43]
	v_mfma_f32_16x16x32_bf16 v[28:31], v[132:135], v[234:237], v[28:31]
	v_mfma_f32_16x16x32_bf16 v[24:27], v[140:143], v[234:237], v[24:27]
	v_mfma_f32_16x16x32_bf16 v[12:15], v[132:135], v[242:245], v[12:15]
	v_mfma_f32_16x16x32_bf16 v[8:11], v[140:143], v[242:245], v[8:11]
	s_setprio 0
	s_setprio 1
	v_mfma_f32_16x16x32_bf16 v[52:55], v[174:177], v[214:217], v[52:55]
	v_mfma_f32_16x16x32_bf16 v[48:51], v[188:191], v[214:217], v[48:51]
	v_mfma_f32_16x16x32_bf16 v[36:39], v[174:177], v[222:225], v[36:39]
	v_mfma_f32_16x16x32_bf16 v[32:35], v[188:191], v[222:225], v[32:35]
	v_mfma_f32_16x16x32_bf16 v[20:23], v[174:177], v[230:233], v[20:23]
	v_mfma_f32_16x16x32_bf16 v[16:19], v[188:191], v[230:233], v[16:19]
	v_mfma_f32_16x16x32_bf16 v[4:7], v[174:177], v[238:241], v[4:7]
	v_mfma_f32_16x16x32_bf16 v[0:3], v[188:191], v[238:241], v[0:3]
	v_mfma_f32_16x16x32_bf16 v[52:55], v[184:187], v[218:221], v[52:55]
	v_mfma_f32_16x16x32_bf16 v[48:51], v[210:213], v[218:221], v[48:51]
	v_mfma_f32_16x16x32_bf16 v[36:39], v[184:187], v[226:229], v[36:39]
	v_mfma_f32_16x16x32_bf16 v[32:35], v[210:213], v[226:229], v[32:35]
	s_setprio 0
	s_barrier
	v_mfma_f32_16x16x32_bf16 v[20:23], v[184:187], v[234:237], v[20:23]
	v_mfma_f32_16x16x32_bf16 v[16:19], v[210:213], v[234:237], v[16:19]
	v_mfma_f32_16x16x32_bf16 v[4:7], v[184:187], v[242:245], v[4:7]
	v_mfma_f32_16x16x32_bf16 v[0:3], v[210:213], v[242:245], v[0:3]
	v_or_b32_e32 v128, 0x18000, v182
	v_add_u32_e32 v132, 0x18400, v182
	v_add_u32_e32 v136, 0x18800, v182
	v_add_u32_e32 v140, 0x18c00, v182
	v_or_b32_e32 v174, 0x1c000, v182
	v_add_u32_e32 v183, 0x1c400, v182
	ds_read_b128 v[128:131], v128
	ds_read_b128 v[132:135], v132
	ds_read_b128 v[136:139], v136
	ds_read_b128 v[140:143], v140
	ds_read_b128 v[174:177], v174
	ds_read_b128 v[184:187], v183
	v_add_u32_e32 v183, 0x1c800, v182
	v_add_u32_e32 v210, 0x1cc00, v182
	ds_read_b128 v[188:191], v183
	ds_read_b128 v[210:213], v210
	s_add_u32 s0, s6, 0xb0000
	s_addc_u32 s1, s7, 0
	s_mov_b32 m0, s42
	v_lshl_add_u64 v[250:251], s[0:1], 0, v[168:169]
	ds_read_b128 v[214:217], v181 offset:32768
	ds_read_b128 v[218:221], v181 offset:33792
	ds_read_b128 v[222:225], v181 offset:34816
	ds_read_b128 v[226:229], v181 offset:35840
	ds_read_b128 v[230:233], v181 offset:36864
	ds_read_b128 v[234:237], v181 offset:37888
	ds_read_b128 v[238:241], v181 offset:38912
	ds_read_b128 v[242:245], v181 offset:39936
	global_load_lds_dwordx4 v[250:251], off
	v_lshl_add_u64 v[250:251], s[0:1], 0, v[164:165]
	s_mov_b32 m0, s43
	s_nop 0
	global_load_lds_dwordx4 v[250:251], off
	s_waitcnt vmcnt(8)
	s_waitcnt lgkmcnt(0)
	s_barrier
	s_setprio 1
	s_waitcnt lgkmcnt(0)
	v_mfma_f32_16x16x32_bf16 v[124:127], v[128:131], v[214:217], v[124:127]
	v_mfma_f32_16x16x32_bf16 v[120:123], v[136:139], v[214:217], v[120:123]
	v_mfma_f32_16x16x32_bf16 v[108:111], v[128:131], v[222:225], v[108:111]
	v_mfma_f32_16x16x32_bf16 v[104:107], v[136:139], v[222:225], v[104:107]
	v_mfma_f32_16x16x32_bf16 v[92:95], v[128:131], v[230:233], v[92:95]
	v_mfma_f32_16x16x32_bf16 v[88:91], v[136:139], v[230:233], v[88:91]
	v_mfma_f32_16x16x32_bf16 v[76:79], v[128:131], v[238:241], v[76:79]
	v_mfma_f32_16x16x32_bf16 v[72:75], v[136:139], v[238:241], v[72:75]
	v_mfma_f32_16x16x32_bf16 v[124:127], v[132:135], v[218:221], v[124:127]
	v_mfma_f32_16x16x32_bf16 v[120:123], v[140:143], v[218:221], v[120:123]
	v_mfma_f32_16x16x32_bf16 v[108:111], v[132:135], v[226:229], v[108:111]
	v_mfma_f32_16x16x32_bf16 v[104:107], v[140:143], v[226:229], v[104:107]
	v_mfma_f32_16x16x32_bf16 v[92:95], v[132:135], v[234:237], v[92:95]
	v_mfma_f32_16x16x32_bf16 v[88:91], v[140:143], v[234:237], v[88:91]
	v_mfma_f32_16x16x32_bf16 v[76:79], v[132:135], v[242:245], v[76:79]
	v_mfma_f32_16x16x32_bf16 v[72:75], v[140:143], v[242:245], v[72:75]
	s_setprio 0
	s_setprio 1
	v_mfma_f32_16x16x32_bf16 v[116:119], v[174:177], v[214:217], v[116:119]
	v_mfma_f32_16x16x32_bf16 v[112:115], v[188:191], v[214:217], v[112:115]
	v_mfma_f32_16x16x32_bf16 v[100:103], v[174:177], v[222:225], v[100:103]
	v_mfma_f32_16x16x32_bf16 v[96:99], v[188:191], v[222:225], v[96:99]
	v_mfma_f32_16x16x32_bf16 v[84:87], v[174:177], v[230:233], v[84:87]
	v_mfma_f32_16x16x32_bf16 v[80:83], v[188:191], v[230:233], v[80:83]
	v_mfma_f32_16x16x32_bf16 v[68:71], v[174:177], v[238:241], v[68:71]
	v_mfma_f32_16x16x32_bf16 v[64:67], v[188:191], v[238:241], v[64:67]
	v_mfma_f32_16x16x32_bf16 v[116:119], v[184:187], v[218:221], v[116:119]
	v_mfma_f32_16x16x32_bf16 v[112:115], v[210:213], v[218:221], v[112:115]
	v_mfma_f32_16x16x32_bf16 v[100:103], v[184:187], v[226:229], v[100:103]
	v_mfma_f32_16x16x32_bf16 v[96:99], v[210:213], v[226:229], v[96:99]
	s_setprio 0
	s_barrier
; #define PG8_STAGE(bufoff, gbase, voff) do { _Pragma("unroll") for (int _i = 0; _i < 2; ++_i) \
;         __builtin_amdgcn_global_load_lds((const unsigned*)((const char*)(gbase) + (voff)[_i]), (PG8_LAS unsigned*)(lds + (bufoff) + ldsw + _i * 8192), 16, 0, 0); } while (0)
; #define PG8_LDA(dst, b, h) do { _Pragma("unroll") for (int m = 0; m < 4; ++m) _Pragma("unroll") for (int k = 0; k < 2; ++k) dst[m][k] = *(const PG8_LAS bf16x8*)(lds + PG8_SA(b, h) + aoff + m * 2048 + k * 1024); } while (0)
; #define PG8_MMA(ai, bj, At, Bt) do { __builtin_amdgcn_s_setprio(1); _Pragma("unroll") for (int m = 0; m < 4; ++m) _Pragma("unroll") for (int n = 0; n < 2; ++n) _Pragma("unroll") for (int k = 0; k < 2; ++k) \
;         acc[ai][bj][m][n] = __builtin_amdgcn_mfma_f32_16x16x32_bf16(Bt[n][k], At[m][k], acc[ai][bj][m][n], 0, 0, 0); __builtin_amdgcn_s_setprio(0); } while (0)
; #define PG8_WAIT_V(n) asm volatile("s_waitcnt vmcnt(" #n ")" ::: "memory")
; #define PG8_WAIT_L(n) asm volatile("s_waitcnt lgkmcnt(" #n ")" ::: "memory")
; #define PG8_BAR __builtin_amdgcn_s_barrier()
; #define PG8_SCHED __builtin_amdgcn_sched_barrier(0)
; template <class Epi, class Sched, bool ALIGN_EPI = false, bool SP2 = false>
; __device__ __forceinline__ void gemm_phase(PG8_LAS unsigned char* lds, const Gemm g, const Sched& S, const Epi& E) {
;     ...
;             PG8_WAIT_V(8); PG8_WAIT_L(0); PG8_BAR; PG8_MMA(0, 0, At, B0); PG8_MMA(0, 1, At, B1); PG8_BAR; PG8_SCHED;
;             PG8_LDA(At, 1, 1); PG8_STAGE(PG8_SB(1, 0), b3, voffB); PG8_STAGE(PG8_SB(1, 1), b3 + hstep, voffB); PG8_STAGE(PG8_SA(1, 0), a3, voffA);
;             PG8_WAIT_V(8); PG8_WAIT_L(0); PG8_BAR; PG8_MMA(1, 0, At, B0); PG8_MMA(1, 1, At, B1); PG8_BAR; PG8_SCHED;
;     ...
;         if constexpr (ALIGN_EPI) { if (wr == 0) PG8_BAR; }
	v_mfma_f32_16x16x32_bf16 v[84:87], v[184:187], v[234:237], v[84:87]
	v_mfma_f32_16x16x32_bf16 v[80:83], v[210:213], v[234:237], v[80:83]
	v_mfma_f32_16x16x32_bf16 v[68:71], v[184:187], v[242:245], v[68:71]
	v_mfma_f32_16x16x32_bf16 v[64:67], v[210:213], v[242:245], v[64:67]
	s_mov_b32 m0, s47
	v_lshl_add_u64 v[178:179], v[178:179], 0, s[94:95]
	s_add_u32 s0, s4, 0xb0080
	ds_read_b128 v[214:217], v181 offset:49152
	ds_read_b128 v[218:221], v181 offset:50176
	ds_read_b128 v[222:225], v181 offset:51200
	ds_read_b128 v[226:229], v181 offset:52224
	ds_read_b128 v[230:233], v181 offset:53248
	ds_read_b128 v[234:237], v181 offset:54272
	ds_read_b128 v[238:241], v181 offset:55296
	ds_read_b128 v[242:245], v181 offset:56320
	global_load_lds_dwordx4 v[178:179], off
	v_lshl_add_u64 v[178:179], v[208:209], 0, s[94:95]
	s_mov_b32 m0, s48
	s_addc_u32 s1, s5, 0
	global_load_lds_dwordx4 v[178:179], off
	v_lshl_add_u64 v[178:179], s[0:1], 0, v[166:167]
	s_mov_b32 m0, s51
	s_nop 0
	global_load_lds_dwordx4 v[178:179], off
	v_lshl_add_u64 v[178:179], s[0:1], 0, v[162:163]
	s_mov_b32 m0, s52
	s_nop 0
	global_load_lds_dwordx4 v[178:179], off
	v_lshl_add_u64 v[178:179], v[246:247], 0, s[94:95]
	s_mov_b32 m0, s49
	s_nop 0
	global_load_lds_dwordx4 v[178:179], off
	v_lshl_add_u64 v[178:179], v[248:249], 0, s[94:95]
	s_mov_b32 m0, s50
	s_nop 0
	global_load_lds_dwordx4 v[178:179], off
	s_waitcnt vmcnt(8)
	s_waitcnt lgkmcnt(0)
	s_barrier
	s_setprio 1
	s_waitcnt lgkmcnt(0)
	v_mfma_f32_16x16x32_bf16 v[60:63], v[128:131], v[214:217], v[60:63]
	v_mfma_f32_16x16x32_bf16 v[56:59], v[136:139], v[214:217], v[56:59]
	v_mfma_f32_16x16x32_bf16 v[44:47], v[128:131], v[222:225], v[44:47]
	v_mfma_f32_16x16x32_bf16 v[40:43], v[136:139], v[222:225], v[40:43]
	v_mfma_f32_16x16x32_bf16 v[28:31], v[128:131], v[230:233], v[28:31]
	v_mfma_f32_16x16x32_bf16 v[24:27], v[136:139], v[230:233], v[24:27]
	v_mfma_f32_16x16x32_bf16 v[12:15], v[128:131], v[238:241], v[12:15]
	v_mfma_f32_16x16x32_bf16 v[8:11], v[136:139], v[238:241], v[8:11]
	v_mfma_f32_16x16x32_bf16 v[60:63], v[132:135], v[218:221], v[60:63]
	v_mfma_f32_16x16x32_bf16 v[56:59], v[140:143], v[218:221], v[56:59]
	v_mfma_f32_16x16x32_bf16 v[44:47], v[132:135], v[226:229], v[44:47]
	v_mfma_f32_16x16x32_bf16 v[40:43], v[140:143], v[226:229], v[40:43]
	v_mfma_f32_16x16x32_bf16 v[28:31], v[132:135], v[234:237], v[28:31]
	v_mfma_f32_16x16x32_bf16 v[24:27], v[140:143], v[234:237], v[24:27]
	v_mfma_f32_16x16x32_bf16 v[12:15], v[132:135], v[242:245], v[12:15]
	v_mfma_f32_16x16x32_bf16 v[8:11], v[140:143], v[242:245], v[8:11]
	s_setprio 0
	s_setprio 1
	v_mfma_f32_16x16x32_bf16 v[52:55], v[174:177], v[214:217], v[52:55]
	v_mfma_f32_16x16x32_bf16 v[48:51], v[188:191], v[214:217], v[48:51]
	v_mfma_f32_16x16x32_bf16 v[36:39], v[174:177], v[222:225], v[36:39]
	v_mfma_f32_16x16x32_bf16 v[32:35], v[188:191], v[222:225], v[32:35]
	v_mfma_f32_16x16x32_bf16 v[20:23], v[174:177], v[230:233], v[20:23]
	v_mfma_f32_16x16x32_bf16 v[16:19], v[188:191], v[230:233], v[16:19]
	v_mfma_f32_16x16x32_bf16 v[4:7], v[174:177], v[238:241], v[4:7]
	v_mfma_f32_16x16x32_bf16 v[0:3], v[188:191], v[238:241], v[0:3]
	v_mfma_f32_16x16x32_bf16 v[52:55], v[184:187], v[218:221], v[52:55]
	v_mfma_f32_16x16x32_bf16 v[48:51], v[210:213], v[218:221], v[48:51]
	v_mfma_f32_16x16x32_bf16 v[36:39], v[184:187], v[226:229], v[36:39]
	v_mfma_f32_16x16x32_bf16 v[32:35], v[210:213], v[226:229], v[32:35]
	s_setprio 0
	s_barrier
	v_mfma_f32_16x16x32_bf16 v[20:23], v[184:187], v[234:237], v[20:23]
	v_mfma_f32_16x16x32_bf16 v[16:19], v[210:213], v[234:237], v[16:19]
	v_mfma_f32_16x16x32_bf16 v[4:7], v[184:187], v[242:245], v[4:7]
	v_mfma_f32_16x16x32_bf16 v[0:3], v[210:213], v[242:245], v[0:3]
	s_add_i32 s13, s13, 2
	s_add_u32 s10, s10, 0x100
	s_addc_u32 s11, s11, 0
	s_cmp_gt_u32 s13, 41
	s_mov_b64 s[0:1], s[2:3]
	s_cbranch_scc0 .LBB0_545
	s_and_b64 vcc, exec, s[22:23]
	s_cbranch_vccz .LBB0_548
	s_barrier

; #define PG8_STAGE(bufoff, gbase, voff) do { _Pragma("unroll") for (int _i = 0; _i < 2; ++_i) \
;         __builtin_amdgcn_global_load_lds((const unsigned*)((const char*)(gbase) + (voff)[_i]), (PG8_LAS unsigned*)(lds + (bufoff) + ldsw + _i * 8192), 16, 0, 0); } while (0)
; #define PG8_LDA(dst, b, h) do { _Pragma("unroll") for (int m = 0; m < 4; ++m) _Pragma("unroll") for (int k = 0; k < 2; ++k) dst[m][k] = *(const PG8_LAS bf16x8*)(lds + PG8_SA(b, h) + aoff + m * 2048 + k * 1024); } while (0)
; #define PG8_LDB(dst, b, h) do { _Pragma("unroll") for (int n = 0; n < 2; ++n) _Pragma("unroll") for (int k = 0; k < 2; ++k) dst[n][k] = *(const PG8_LAS bf16x8*)(lds + PG8_SB(b, h) + boff + n * 2048 + k * 1024); } while (0)
; #define PG8_MMA(ai, bj, At, Bt) do { __builtin_amdgcn_s_setprio(1); _Pragma("unroll") for (int m = 0; m < 4; ++m) _Pragma("unroll") for (int n = 0; n < 2; ++n) _Pragma("unroll") for (int k = 0; k < 2; ++k) \
;         acc[ai][bj][m][n] = __builtin_amdgcn_mfma_f32_16x16x32_bf16(Bt[n][k], At[m][k], acc[ai][bj][m][n], 0, 0, 0); __builtin_amdgcn_s_setprio(0); } while (0)
; #define PG8_WAIT_V(n) asm volatile("s_waitcnt vmcnt(" #n ")" ::: "memory")
; #define PG8_WAIT_L(n) asm volatile("s_waitcnt lgkmcnt(" #n ")" ::: "memory")
; #define PG8_BAR __builtin_amdgcn_s_barrier()
; #define PG8_SCHED __builtin_amdgcn_sched_barrier(0)
; template <class Epi, class Sched, bool ALIGN_EPI = false, bool SP2 = false>
; __device__ __forceinline__ void gemm_phase(PG8_LAS unsigned char* lds, const Gemm g, const Sched& S, const Epi& E) {
;     ...
;             PG8_LDB(B0, 0, 0); PG8_LDB(B1, 0, 1); PG8_SCHED; PG8_LDA(At, 0, 0); PG8_STAGE(PG8_SA(1, 1), a1 + hstep, voffA);
;             PG8_WAIT_V(8); PG8_WAIT_L(0); PG8_BAR; PG8_MMA(0, 0, At, B0); PG8_MMA(0, 1, At, B1); PG8_BAR; PG8_SCHED;
;             PG8_LDA(At, 0, 1); PG8_STAGE(PG8_SB(0, 0), b2, voffB); PG8_STAGE(PG8_SB(0, 1), b2 + hstep, voffB); PG8_STAGE(PG8_SA(0, 0), a2, voffA);
;             PG8_WAIT_V(8); PG8_WAIT_L(0); PG8_BAR; PG8_MMA(1, 0, At, B0); PG8_MMA(1, 1, At, B1); PG8_BAR; PG8_SCHED;
.LBB0_749:
	v_or_b32_e32 v140, 0x10000, v179
	v_add_u32_e32 v147, 0x10400, v179
	ds_read_b128 v[140:143], v140
	ds_read_b128 v[162:165], v147
	v_add_u32_e32 v147, 0x10800, v179
	v_add_u32_e32 v170, 0x10c00, v179
	ds_read_b128 v[166:169], v147
	ds_read_b128 v[170:173], v170
	v_or_b32_e32 v147, 0x14000, v179
	v_add_u32_e32 v174, 0x14400, v179
	ds_read_b128 v[180:183], v147
	ds_read_b128 v[184:187], v174
	v_add_u32_e32 v147, 0x14800, v179
	v_add_u32_e32 v174, 0x14c00, v179
	ds_read_b128 v[188:191], v147
	ds_read_b128 v[210:213], v174
	s_add_u32 s2, s0, 0xfffc0080
	s_addc_u32 s3, s1, -1
	s_cmp_eq_u32 s55, 12
	s_cselect_b32 s5, s13, s3
	s_cselect_b32 s4, s25, s2
	s_cselect_b32 s3, s23, s39
	s_cselect_b32 s2, s33, s38
	v_lshl_add_u64 v[174:175], s[0:1], 0, v[136:137]
	s_add_i32 m0, s6, 0xc000
	ds_read_b128 v[214:217], v178
	ds_read_b128 v[218:221], v178 offset:1024
	ds_read_b128 v[222:225], v178 offset:2048
	ds_read_b128 v[226:229], v178 offset:3072
	ds_read_b128 v[230:233], v178 offset:4096
	ds_read_b128 v[234:237], v178 offset:5120
	ds_read_b128 v[238:241], v178 offset:6144
	ds_read_b128 v[242:245], v178 offset:7168
	global_load_lds_dwordx4 v[174:175], off
	v_lshl_add_u64 v[174:175], s[0:1], 0, v[138:139]
	s_add_i32 m0, s6, 0xe000
	s_nop 0
	global_load_lds_dwordx4 v[174:175], off
	s_waitcnt vmcnt(8)
	s_waitcnt lgkmcnt(0)
	s_barrier
	s_setprio 1
	s_waitcnt lgkmcnt(0)
	v_mfma_f32_16x16x32_bf16 v[124:127], v[140:143], v[214:217], v[124:127]
	v_mfma_f32_16x16x32_bf16 v[120:123], v[166:169], v[214:217], v[120:123]
	v_mfma_f32_16x16x32_bf16 v[108:111], v[140:143], v[222:225], v[108:111]
	v_mfma_f32_16x16x32_bf16 v[104:107], v[166:169], v[222:225], v[104:107]
	v_mfma_f32_16x16x32_bf16 v[92:95], v[140:143], v[230:233], v[92:95]
	v_mfma_f32_16x16x32_bf16 v[88:91], v[166:169], v[230:233], v[88:91]
	v_mfma_f32_16x16x32_bf16 v[76:79], v[140:143], v[238:241], v[76:79]
	v_mfma_f32_16x16x32_bf16 v[72:75], v[166:169], v[238:241], v[72:75]
	v_mfma_f32_16x16x32_bf16 v[124:127], v[162:165], v[218:221], v[124:127]
	v_mfma_f32_16x16x32_bf16 v[120:123], v[170:173], v[218:221], v[120:123]
	v_mfma_f32_16x16x32_bf16 v[108:111], v[162:165], v[226:229], v[108:111]
	v_mfma_f32_16x16x32_bf16 v[104:107], v[170:173], v[226:229], v[104:107]
	v_mfma_f32_16x16x32_bf16 v[92:95], v[162:165], v[234:237], v[92:95]
	v_mfma_f32_16x16x32_bf16 v[88:91], v[170:173], v[234:237], v[88:91]
	v_mfma_f32_16x16x32_bf16 v[76:79], v[162:165], v[242:245], v[76:79]
	v_mfma_f32_16x16x32_bf16 v[72:75], v[170:173], v[242:245], v[72:75]
	s_setprio 0
	s_setprio 1
	v_mfma_f32_16x16x32_bf16 v[116:119], v[180:183], v[214:217], v[116:119]
	v_mfma_f32_16x16x32_bf16 v[112:115], v[188:191], v[214:217], v[112:115]
	v_mfma_f32_16x16x32_bf16 v[100:103], v[180:183], v[222:225], v[100:103]
	v_mfma_f32_16x16x32_bf16 v[96:99], v[188:191], v[222:225], v[96:99]
	v_mfma_f32_16x16x32_bf16 v[84:87], v[180:183], v[230:233], v[84:87]
	v_mfma_f32_16x16x32_bf16 v[80:83], v[188:191], v[230:233], v[80:83]
	v_mfma_f32_16x16x32_bf16 v[68:71], v[180:183], v[238:241], v[68:71]
	v_mfma_f32_16x16x32_bf16 v[64:67], v[188:191], v[238:241], v[64:67]
	v_mfma_f32_16x16x32_bf16 v[116:119], v[184:187], v[218:221], v[116:119]
	v_mfma_f32_16x16x32_bf16 v[112:115], v[210:213], v[218:221], v[112:115]
	v_mfma_f32_16x16x32_bf16 v[100:103], v[184:187], v[226:229], v[100:103]
	v_mfma_f32_16x16x32_bf16 v[96:99], v[210:213], v[226:229], v[96:99]
	s_setprio 0
	s_barrier
	v_mfma_f32_16x16x32_bf16 v[84:87], v[184:187], v[234:237], v[84:87]
	v_mfma_f32_16x16x32_bf16 v[80:83], v[210:213], v[234:237], v[80:83]
	v_mfma_f32_16x16x32_bf16 v[68:71], v[184:187], v[242:245], v[68:71]
	v_mfma_f32_16x16x32_bf16 v[64:67], v[210:213], v[242:245], v[64:67]
	s_mov_b32 m0, s31
	v_lshl_add_u64 v[174:175], s[2:3], 0, v[132:133]
	s_add_u32 s56, s2, 0x40000
	ds_read_b128 v[214:217], v178 offset:16384
	ds_read_b128 v[218:221], v178 offset:17408
	ds_read_b128 v[222:225], v178 offset:18432
	ds_read_b128 v[226:229], v178 offset:19456
	ds_read_b128 v[230:233], v178 offset:20480
	ds_read_b128 v[234:237], v178 offset:21504
	ds_read_b128 v[238:241], v178 offset:22528
	ds_read_b128 v[242:245], v178 offset:23552
	global_load_lds_dwordx4 v[174:175], off
	v_lshl_add_u64 v[208:209], s[2:3], 0, v[128:129]
	s_mov_b32 m0, s34
	s_addc_u32 s57, s3, 0
	global_load_lds_dwordx4 v[208:209], off
	v_lshl_add_u64 v[246:247], s[56:57], 0, v[132:133]
	s_mov_b32 m0, s35
	v_lshl_add_u64 v[248:249], s[4:5], 0, v[130:131]
	global_load_lds_dwordx4 v[246:247], off
	v_lshl_add_u64 v[246:247], s[56:57], 0, v[128:129]
	s_mov_b32 m0, s40
	s_nop 0
	global_load_lds_dwordx4 v[246:247], off
	v_lshl_add_u64 v[246:247], s[4:5], 0, v[134:135]
	s_mov_b32 m0, s6
	s_nop 0
	global_load_lds_dwordx4 v[246:247], off
	s_mov_b32 m0, s41
	s_nop 0
	global_load_lds_dwordx4 v[248:249], off
	s_waitcnt vmcnt(8)
	s_waitcnt lgkmcnt(0)
	s_barrier
; #define PG8_STAGE(bufoff, gbase, voff) do { _Pragma("unroll") for (int _i = 0; _i < 2; ++_i) \
;         __builtin_amdgcn_global_load_lds((const unsigned*)((const char*)(gbase) + (voff)[_i]), (PG8_LAS unsigned*)(lds + (bufoff) + ldsw + _i * 8192), 16, 0, 0); } while (0)
; #define PG8_LDA(dst, b, h) do { _Pragma("unroll") for (int m = 0; m < 4; ++m) _Pragma("unroll") for (int k = 0; k < 2; ++k) dst[m][k] = *(const PG8_LAS bf16x8*)(lds + PG8_SA(b, h) + aoff + m * 2048 + k * 1024); } while (0)
; #define PG8_LDB(dst, b, h) do { _Pragma("unroll") for (int n = 0; n < 2; ++n) _Pragma("unroll") for (int k = 0; k < 2; ++k) dst[n][k] = *(const PG8_LAS bf16x8*)(lds + PG8_SB(b, h) + boff + n * 2048 + k * 1024); } while (0)
; #define PG8_MMA(ai, bj, At, Bt) do { __builtin_amdgcn_s_setprio(1); _Pragma("unroll") for (int m = 0; m < 4; ++m) _Pragma("unroll") for (int n = 0; n < 2; ++n) _Pragma("unroll") for (int k = 0; k < 2; ++k) \
;         acc[ai][bj][m][n] = __builtin_amdgcn_mfma_f32_16x16x32_bf16(Bt[n][k], At[m][k], acc[ai][bj][m][n], 0, 0, 0); __builtin_amdgcn_s_setprio(0); } while (0)
; #define PG8_WAIT_V(n) asm volatile("s_waitcnt vmcnt(" #n ")" ::: "memory")
; #define PG8_WAIT_L(n) asm volatile("s_waitcnt lgkmcnt(" #n ")" ::: "memory")
; #define PG8_BAR __builtin_amdgcn_s_barrier()
; #define PG8_SCHED __builtin_amdgcn_sched_barrier(0)
; template <class Epi, class Sched, bool ALIGN_EPI = false, bool SP2 = false>
; __device__ __forceinline__ void gemm_phase(PG8_LAS unsigned char* lds, const Gemm g, const Sched& S, const Epi& E) {
;     ...
;             PG8_WAIT_V(8); PG8_WAIT_L(0); PG8_BAR; PG8_MMA(1, 0, At, B0); PG8_MMA(1, 1, At, B1); PG8_BAR; PG8_SCHED;
;             PG8_LDB(B0, 1, 0); PG8_LDB(B1, 1, 1); PG8_SCHED; PG8_LDA(At, 1, 0); PG8_STAGE(PG8_SA(0, 1), a2 + hstep, voffA);
;             PG8_WAIT_V(8); PG8_WAIT_L(0); PG8_BAR; PG8_MMA(0, 0, At, B0); PG8_MMA(0, 1, At, B1); PG8_BAR; PG8_SCHED;
	s_setprio 1
	s_waitcnt lgkmcnt(0)
	v_mfma_f32_16x16x32_bf16 v[60:63], v[140:143], v[214:217], v[60:63]
	v_mfma_f32_16x16x32_bf16 v[56:59], v[166:169], v[214:217], v[56:59]
	v_mfma_f32_16x16x32_bf16 v[44:47], v[140:143], v[222:225], v[44:47]
	v_mfma_f32_16x16x32_bf16 v[40:43], v[166:169], v[222:225], v[40:43]
	v_mfma_f32_16x16x32_bf16 v[28:31], v[140:143], v[230:233], v[28:31]
	v_mfma_f32_16x16x32_bf16 v[24:27], v[166:169], v[230:233], v[24:27]
	v_mfma_f32_16x16x32_bf16 v[12:15], v[140:143], v[238:241], v[12:15]
	v_mfma_f32_16x16x32_bf16 v[8:11], v[166:169], v[238:241], v[8:11]
	v_mfma_f32_16x16x32_bf16 v[60:63], v[162:165], v[218:221], v[60:63]
	v_mfma_f32_16x16x32_bf16 v[56:59], v[170:173], v[218:221], v[56:59]
	v_mfma_f32_16x16x32_bf16 v[44:47], v[162:165], v[226:229], v[44:47]
	v_mfma_f32_16x16x32_bf16 v[40:43], v[170:173], v[226:229], v[40:43]
	v_mfma_f32_16x16x32_bf16 v[28:31], v[162:165], v[234:237], v[28:31]
	v_mfma_f32_16x16x32_bf16 v[24:27], v[170:173], v[234:237], v[24:27]
	v_mfma_f32_16x16x32_bf16 v[12:15], v[162:165], v[242:245], v[12:15]
	v_mfma_f32_16x16x32_bf16 v[8:11], v[170:173], v[242:245], v[8:11]
	s_setprio 0
	s_setprio 1
	v_mfma_f32_16x16x32_bf16 v[52:55], v[180:183], v[214:217], v[52:55]
	v_mfma_f32_16x16x32_bf16 v[48:51], v[188:191], v[214:217], v[48:51]
	v_mfma_f32_16x16x32_bf16 v[36:39], v[180:183], v[222:225], v[36:39]
	v_mfma_f32_16x16x32_bf16 v[32:35], v[188:191], v[222:225], v[32:35]
	v_mfma_f32_16x16x32_bf16 v[20:23], v[180:183], v[230:233], v[20:23]
	v_mfma_f32_16x16x32_bf16 v[16:19], v[188:191], v[230:233], v[16:19]
	v_mfma_f32_16x16x32_bf16 v[4:7], v[180:183], v[238:241], v[4:7]
	v_mfma_f32_16x16x32_bf16 v[0:3], v[188:191], v[238:241], v[0:3]
	v_mfma_f32_16x16x32_bf16 v[52:55], v[184:187], v[218:221], v[52:55]
	v_mfma_f32_16x16x32_bf16 v[48:51], v[210:213], v[218:221], v[48:51]
	v_mfma_f32_16x16x32_bf16 v[36:39], v[184:187], v[226:229], v[36:39]
	v_mfma_f32_16x16x32_bf16 v[32:35], v[210:213], v[226:229], v[32:35]
	s_setprio 0
	s_barrier
	v_mfma_f32_16x16x32_bf16 v[20:23], v[184:187], v[234:237], v[20:23]
	v_mfma_f32_16x16x32_bf16 v[16:19], v[210:213], v[234:237], v[16:19]
	v_mfma_f32_16x16x32_bf16 v[4:7], v[184:187], v[242:245], v[4:7]
	v_mfma_f32_16x16x32_bf16 v[0:3], v[210:213], v[242:245], v[0:3]
	v_or_b32_e32 v140, 0x18000, v179
	v_add_u32_e32 v147, 0x18400, v179
	ds_read_b128 v[140:143], v140
	ds_read_b128 v[162:165], v147
	v_add_u32_e32 v147, 0x18800, v179
	v_add_u32_e32 v170, 0x18c00, v179
	ds_read_b128 v[166:169], v147
	ds_read_b128 v[170:173], v170
	v_or_b32_e32 v147, 0x1c000, v179
	v_add_u32_e32 v184, 0x1c400, v179
	ds_read_b128 v[180:183], v147
	ds_read_b128 v[184:187], v184
	v_add_u32_e32 v147, 0x1c800, v179
	v_add_u32_e32 v210, 0x1cc00, v179
	ds_read_b128 v[188:191], v147
	ds_read_b128 v[210:213], v210
	s_add_u32 s4, s4, 0x40000
	s_addc_u32 s5, s5, 0
	s_mov_b32 m0, s42
	v_lshl_add_u64 v[250:251], s[4:5], 0, v[134:135]
	ds_read_b128 v[214:217], v178 offset:32768
	ds_read_b128 v[218:221], v178 offset:33792
	ds_read_b128 v[222:225], v178 offset:34816
	ds_read_b128 v[226:229], v178 offset:35840
	ds_read_b128 v[230:233], v178 offset:36864
	ds_read_b128 v[234:237], v178 offset:37888
	ds_read_b128 v[238:241], v178 offset:38912
	ds_read_b128 v[242:245], v178 offset:39936
	global_load_lds_dwordx4 v[250:251], off
	v_lshl_add_u64 v[250:251], s[4:5], 0, v[130:131]
	s_mov_b32 m0, s43
	s_nop 0
	global_load_lds_dwordx4 v[250:251], off
	s_waitcnt vmcnt(8)
	s_waitcnt lgkmcnt(0)
	s_barrier
	s_setprio 1
	s_waitcnt lgkmcnt(0)
	v_mfma_f32_16x16x32_bf16 v[124:127], v[140:143], v[214:217], v[124:127]
	v_mfma_f32_16x16x32_bf16 v[120:123], v[166:169], v[214:217], v[120:123]
	v_mfma_f32_16x16x32_bf16 v[108:111], v[140:143], v[222:225], v[108:111]
	v_mfma_f32_16x16x32_bf16 v[104:107], v[166:169], v[222:225], v[104:107]
	v_mfma_f32_16x16x32_bf16 v[92:95], v[140:143], v[230:233], v[92:95]
	v_mfma_f32_16x16x32_bf16 v[88:91], v[166:169], v[230:233], v[88:91]
	v_mfma_f32_16x16x32_bf16 v[76:79], v[140:143], v[238:241], v[76:79]
	v_mfma_f32_16x16x32_bf16 v[72:75], v[166:169], v[238:241], v[72:75]
	v_mfma_f32_16x16x32_bf16 v[124:127], v[162:165], v[218:221], v[124:127]
	v_mfma_f32_16x16x32_bf16 v[120:123], v[170:173], v[218:221], v[120:123]
	v_mfma_f32_16x16x32_bf16 v[108:111], v[162:165], v[226:229], v[108:111]
	v_mfma_f32_16x16x32_bf16 v[104:107], v[170:173], v[226:229], v[104:107]
	v_mfma_f32_16x16x32_bf16 v[92:95], v[162:165], v[234:237], v[92:95]
	v_mfma_f32_16x16x32_bf16 v[88:91], v[170:173], v[234:237], v[88:91]
	v_mfma_f32_16x16x32_bf16 v[76:79], v[162:165], v[242:245], v[76:79]
	v_mfma_f32_16x16x32_bf16 v[72:75], v[170:173], v[242:245], v[72:75]
	s_setprio 0
	s_setprio 1
	v_mfma_f32_16x16x32_bf16 v[116:119], v[180:183], v[214:217], v[116:119]
	v_mfma_f32_16x16x32_bf16 v[112:115], v[188:191], v[214:217], v[112:115]
	v_mfma_f32_16x16x32_bf16 v[100:103], v[180:183], v[222:225], v[100:103]
	v_mfma_f32_16x16x32_bf16 v[96:99], v[188:191], v[222:225], v[96:99]
	v_mfma_f32_16x16x32_bf16 v[84:87], v[180:183], v[230:233], v[84:87]
	v_mfma_f32_16x16x32_bf16 v[80:83], v[188:191], v[230:233], v[80:83]
	v_mfma_f32_16x16x32_bf16 v[68:71], v[180:183], v[238:241], v[68:71]
	v_mfma_f32_16x16x32_bf16 v[64:67], v[188:191], v[238:241], v[64:67]
	v_mfma_f32_16x16x32_bf16 v[116:119], v[184:187], v[218:221], v[116:119]
	v_mfma_f32_16x16x32_bf16 v[112:115], v[210:213], v[218:221], v[112:115]
	v_mfma_f32_16x16x32_bf16 v[100:103], v[184:187], v[226:229], v[100:103]
	v_mfma_f32_16x16x32_bf16 v[96:99], v[210:213], v[226:229], v[96:99]
	s_setprio 0
	s_barrier
; #define PG8_STAGE(bufoff, gbase, voff) do { _Pragma("unroll") for (int _i = 0; _i < 2; ++_i) \
;         __builtin_amdgcn_global_load_lds((const unsigned*)((const char*)(gbase) + (voff)[_i]), (PG8_LAS unsigned*)(lds + (bufoff) + ldsw + _i * 8192), 16, 0, 0); } while (0)
; #define PG8_LDA(dst, b, h) do { _Pragma("unroll") for (int m = 0; m < 4; ++m) _Pragma("unroll") for (int k = 0; k < 2; ++k) dst[m][k] = *(const PG8_LAS bf16x8*)(lds + PG8_SA(b, h) + aoff + m * 2048 + k * 1024); } while (0)
; #define PG8_MMA(ai, bj, At, Bt) do { __builtin_amdgcn_s_setprio(1); _Pragma("unroll") for (int m = 0; m < 4; ++m) _Pragma("unroll") for (int n = 0; n < 2; ++n) _Pragma("unroll") for (int k = 0; k < 2; ++k) \
;         acc[ai][bj][m][n] = __builtin_amdgcn_mfma_f32_16x16x32_bf16(Bt[n][k], At[m][k], acc[ai][bj][m][n], 0, 0, 0); __builtin_amdgcn_s_setprio(0); } while (0)
; #define PG8_WAIT_V(n) asm volatile("s_waitcnt vmcnt(" #n ")" ::: "memory")
; #define PG8_WAIT_L(n) asm volatile("s_waitcnt lgkmcnt(" #n ")" ::: "memory")
; #define PG8_BAR __builtin_amdgcn_s_barrier()
; #define PG8_SCHED __builtin_amdgcn_sched_barrier(0)
; template <class Epi, class Sched, bool ALIGN_EPI = false, bool SP2 = false>
; __device__ __forceinline__ void gemm_phase(PG8_LAS unsigned char* lds, const Gemm g, const Sched& S, const Epi& E) {
;     ...
;             PG8_WAIT_V(8); PG8_WAIT_L(0); PG8_BAR; PG8_MMA(0, 0, At, B0); PG8_MMA(0, 1, At, B1); PG8_BAR; PG8_SCHED;
;             PG8_LDA(At, 1, 1); PG8_STAGE(PG8_SB(1, 0), b3, voffB); PG8_STAGE(PG8_SB(1, 1), b3 + hstep, voffB); PG8_STAGE(PG8_SA(1, 0), a3, voffA);
;             PG8_WAIT_V(8); PG8_WAIT_L(0); PG8_BAR; PG8_MMA(1, 0, At, B0); PG8_MMA(1, 1, At, B1); PG8_BAR; PG8_SCHED;
;     ...
;         if constexpr (ALIGN_EPI) { if (wr == 0) PG8_BAR; }
	v_mfma_f32_16x16x32_bf16 v[84:87], v[184:187], v[234:237], v[84:87]
	v_mfma_f32_16x16x32_bf16 v[80:83], v[210:213], v[234:237], v[80:83]
	v_mfma_f32_16x16x32_bf16 v[68:71], v[184:187], v[242:245], v[68:71]
	v_mfma_f32_16x16x32_bf16 v[64:67], v[210:213], v[242:245], v[64:67]
	s_mov_b32 m0, s48
	v_lshl_add_u64 v[174:175], v[174:175], 0, s[94:95]
	s_add_u32 s2, s2, 0x40080
	ds_read_b128 v[214:217], v178 offset:49152
	ds_read_b128 v[218:221], v178 offset:50176
	ds_read_b128 v[222:225], v178 offset:51200
	ds_read_b128 v[226:229], v178 offset:52224
	ds_read_b128 v[230:233], v178 offset:53248
	ds_read_b128 v[234:237], v178 offset:54272
	ds_read_b128 v[238:241], v178 offset:55296
	ds_read_b128 v[242:245], v178 offset:56320
	global_load_lds_dwordx4 v[174:175], off
	v_lshl_add_u64 v[174:175], v[208:209], 0, s[94:95]
	s_mov_b32 m0, s49
	s_addc_u32 s3, s3, 0
	global_load_lds_dwordx4 v[174:175], off
	v_lshl_add_u64 v[174:175], s[2:3], 0, v[132:133]
	s_mov_b32 m0, s52
	s_nop 0
	global_load_lds_dwordx4 v[174:175], off
	v_lshl_add_u64 v[174:175], s[2:3], 0, v[128:129]
	s_mov_b32 m0, s53
	s_nop 0
	global_load_lds_dwordx4 v[174:175], off
	v_lshl_add_u64 v[174:175], v[246:247], 0, s[94:95]
	s_mov_b32 m0, s50
	s_nop 0
	global_load_lds_dwordx4 v[174:175], off
	v_lshl_add_u64 v[174:175], v[248:249], 0, s[94:95]
	s_mov_b32 m0, s51
	s_nop 0
	global_load_lds_dwordx4 v[174:175], off
	s_waitcnt vmcnt(8)
	s_waitcnt lgkmcnt(0)
	s_barrier
	s_setprio 1
	s_waitcnt lgkmcnt(0)
	v_mfma_f32_16x16x32_bf16 v[60:63], v[140:143], v[214:217], v[60:63]
	v_mfma_f32_16x16x32_bf16 v[56:59], v[166:169], v[214:217], v[56:59]
	v_mfma_f32_16x16x32_bf16 v[44:47], v[140:143], v[222:225], v[44:47]
	v_mfma_f32_16x16x32_bf16 v[40:43], v[166:169], v[222:225], v[40:43]
	v_mfma_f32_16x16x32_bf16 v[28:31], v[140:143], v[230:233], v[28:31]
	v_mfma_f32_16x16x32_bf16 v[24:27], v[166:169], v[230:233], v[24:27]
	v_mfma_f32_16x16x32_bf16 v[12:15], v[140:143], v[238:241], v[12:15]
	v_mfma_f32_16x16x32_bf16 v[8:11], v[166:169], v[238:241], v[8:11]
	v_mfma_f32_16x16x32_bf16 v[60:63], v[162:165], v[218:221], v[60:63]
	v_mfma_f32_16x16x32_bf16 v[56:59], v[170:173], v[218:221], v[56:59]
	v_mfma_f32_16x16x32_bf16 v[44:47], v[162:165], v[226:229], v[44:47]
	v_mfma_f32_16x16x32_bf16 v[40:43], v[170:173], v[226:229], v[40:43]
	v_mfma_f32_16x16x32_bf16 v[28:31], v[162:165], v[234:237], v[28:31]
	v_mfma_f32_16x16x32_bf16 v[24:27], v[170:173], v[234:237], v[24:27]
	v_mfma_f32_16x16x32_bf16 v[12:15], v[162:165], v[242:245], v[12:15]
	v_mfma_f32_16x16x32_bf16 v[8:11], v[170:173], v[242:245], v[8:11]
	s_setprio 0
	s_setprio 1
	v_mfma_f32_16x16x32_bf16 v[52:55], v[180:183], v[214:217], v[52:55]
	v_mfma_f32_16x16x32_bf16 v[48:51], v[188:191], v[214:217], v[48:51]
	v_mfma_f32_16x16x32_bf16 v[36:39], v[180:183], v[222:225], v[36:39]
	v_mfma_f32_16x16x32_bf16 v[32:35], v[188:191], v[222:225], v[32:35]
	v_mfma_f32_16x16x32_bf16 v[20:23], v[180:183], v[230:233], v[20:23]
	v_mfma_f32_16x16x32_bf16 v[16:19], v[188:191], v[230:233], v[16:19]
	v_mfma_f32_16x16x32_bf16 v[4:7], v[180:183], v[238:241], v[4:7]
	v_mfma_f32_16x16x32_bf16 v[0:3], v[188:191], v[238:241], v[0:3]
	v_mfma_f32_16x16x32_bf16 v[52:55], v[184:187], v[218:221], v[52:55]
	v_mfma_f32_16x16x32_bf16 v[48:51], v[210:213], v[218:221], v[48:51]
	v_mfma_f32_16x16x32_bf16 v[36:39], v[184:187], v[226:229], v[36:39]
	v_mfma_f32_16x16x32_bf16 v[32:35], v[210:213], v[226:229], v[32:35]
	s_setprio 0
	s_barrier
	v_mfma_f32_16x16x32_bf16 v[20:23], v[184:187], v[234:237], v[20:23]
	v_mfma_f32_16x16x32_bf16 v[16:19], v[210:213], v[234:237], v[16:19]
	v_mfma_f32_16x16x32_bf16 v[4:7], v[184:187], v[242:245], v[4:7]
	v_mfma_f32_16x16x32_bf16 v[0:3], v[210:213], v[242:245], v[0:3]
	s_add_i32 s55, s55, 2
	s_add_u32 s0, s0, 0x100
	s_addc_u32 s1, s1, 0
	s_add_u32 s38, s38, 0x100
	s_addc_u32 s39, s39, 0
	s_cmp_gt_u32 s55, 13
	s_cbranch_scc0 .LBB0_749
	s_and_b64 vcc, exec, s[18:19]
	s_cbranch_vccz .LBB0_752
	s_barrier

; #define PG8_STAGE(bufoff, gbase, voff) do { _Pragma("unroll") for (int _i = 0; _i < 2; ++_i) \
;         __builtin_amdgcn_global_load_lds((const unsigned*)((const char*)(gbase) + (voff)[_i]), (PG8_LAS unsigned*)(lds + (bufoff) + ldsw + _i * 8192), 16, 0, 0); } while (0)
; #define PG8_LDA(dst, b, h) do { _Pragma("unroll") for (int m = 0; m < 4; ++m) _Pragma("unroll") for (int k = 0; k < 2; ++k) dst[m][k] = *(const PG8_LAS bf16x8*)(lds + PG8_SA(b, h) + aoff + m * 2048 + k * 1024); } while (0)
; #define PG8_LDB(dst, b, h) do { _Pragma("unroll") for (int n = 0; n < 2; ++n) _Pragma("unroll") for (int k = 0; k < 2; ++k) dst[n][k] = *(const PG8_LAS bf16x8*)(lds + PG8_SB(b, h) + boff + n * 2048 + k * 1024); } while (0)
; #define PG8_MMA(ai, bj, At, Bt) do { __builtin_amdgcn_s_setprio(1); _Pragma("unroll") for (int m = 0; m < 4; ++m) _Pragma("unroll") for (int n = 0; n < 2; ++n) _Pragma("unroll") for (int k = 0; k < 2; ++k) \
;         acc[ai][bj][m][n] = __builtin_amdgcn_mfma_f32_16x16x32_bf16(Bt[n][k], At[m][k], acc[ai][bj][m][n], 0, 0, 0); __builtin_amdgcn_s_setprio(0); } while (0)
; #define PG8_WAIT_V(n) asm volatile("s_waitcnt vmcnt(" #n ")" ::: "memory")
; #define PG8_WAIT_L(n) asm volatile("s_waitcnt lgkmcnt(" #n ")" ::: "memory")
; #define PG8_BAR __builtin_amdgcn_s_barrier()
; #define PG8_SCHED __builtin_amdgcn_sched_barrier(0)
; template <class Epi, class Sched, bool ALIGN_EPI = false, bool SP2 = false>
; __device__ __forceinline__ void gemm_phase(PG8_LAS unsigned char* lds, const Gemm g, const Sched& S, const Epi& E) {
;     ...
;             PG8_LDB(B0, 0, 0); PG8_LDB(B1, 0, 1); PG8_SCHED; PG8_LDA(At, 0, 0); PG8_STAGE(PG8_SA(1, 1), a1 + hstep, voffA);
;             PG8_WAIT_V(8); PG8_WAIT_L(0); PG8_BAR; PG8_MMA(0, 0, At, B0); PG8_MMA(0, 1, At, B1); PG8_BAR; PG8_SCHED;
;             PG8_LDA(At, 0, 1); PG8_STAGE(PG8_SB(0, 0), b2, voffB); PG8_STAGE(PG8_SB(0, 1), b2 + hstep, voffB); PG8_STAGE(PG8_SA(0, 0), a2, voffA);
;             PG8_WAIT_V(8); PG8_WAIT_L(0); PG8_BAR; PG8_MMA(1, 0, At, B0); PG8_MMA(1, 1, At, B1); PG8_BAR; PG8_SCHED;
.LBB0_792:
	s_waitcnt lgkmcnt(0)
	v_or_b32_e32 v140, 0x10000, v174
	v_add_u32_e32 v162, 0x10400, v174
	v_add_u32_e32 v166, 0x10800, v174
	v_add_u32_e32 v170, 0x10c00, v174
	ds_read_b128 v[140:143], v140
	ds_read_b128 v[162:165], v162
	ds_read_b128 v[166:169], v166
	ds_read_b128 v[176:179], v170
	v_or_b32_e32 v170, 0x14000, v174
	v_add_u32_e32 v171, 0x14400, v174
	ds_read_b128 v[180:183], v170
	ds_read_b128 v[184:187], v171
	v_add_u32_e32 v170, 0x14800, v174
	v_add_u32_e32 v171, 0x14c00, v174
	ds_read_b128 v[188:191], v170
	ds_read_b128 v[210:213], v171
	s_add_u32 s2, s0, 0xfffc0080
	s_addc_u32 s3, s1, -1
	s_cmp_eq_u32 s52, 12
	s_cselect_b32 s5, s17, s3
	s_cselect_b32 s4, s48, s2
	s_cselect_b32 s3, s15, s51
	s_cselect_b32 s2, s49, s50
	v_lshl_add_u64 v[170:171], s[0:1], 0, v[136:137]
	s_add_i32 m0, s6, 0xc000
	ds_read_b128 v[214:217], v173
	ds_read_b128 v[218:221], v173 offset:1024
	ds_read_b128 v[222:225], v173 offset:2048
	ds_read_b128 v[226:229], v173 offset:3072
	ds_read_b128 v[230:233], v173 offset:4096
	ds_read_b128 v[234:237], v173 offset:5120
	ds_read_b128 v[238:241], v173 offset:6144
	ds_read_b128 v[242:245], v173 offset:7168
	global_load_lds_dwordx4 v[170:171], off
	v_lshl_add_u64 v[170:171], s[0:1], 0, v[138:139]
	s_add_i32 m0, s6, 0xe000
	s_nop 0
	global_load_lds_dwordx4 v[170:171], off
	s_waitcnt vmcnt(8)
	s_waitcnt lgkmcnt(0)
	s_barrier
	s_setprio 1
	s_waitcnt lgkmcnt(0)
	v_mfma_f32_16x16x32_bf16 v[124:127], v[140:143], v[214:217], v[124:127]
	v_mfma_f32_16x16x32_bf16 v[120:123], v[166:169], v[214:217], v[120:123]
	v_mfma_f32_16x16x32_bf16 v[112:115], v[140:143], v[222:225], v[112:115]
	v_mfma_f32_16x16x32_bf16 v[104:107], v[166:169], v[222:225], v[104:107]
	v_mfma_f32_16x16x32_bf16 v[96:99], v[140:143], v[230:233], v[96:99]
	v_mfma_f32_16x16x32_bf16 v[88:91], v[166:169], v[230:233], v[88:91]
	v_mfma_f32_16x16x32_bf16 v[80:83], v[140:143], v[238:241], v[80:83]
	v_mfma_f32_16x16x32_bf16 v[72:75], v[166:169], v[238:241], v[72:75]
	v_mfma_f32_16x16x32_bf16 v[124:127], v[162:165], v[218:221], v[124:127]
	v_mfma_f32_16x16x32_bf16 v[120:123], v[176:179], v[218:221], v[120:123]
	v_mfma_f32_16x16x32_bf16 v[112:115], v[162:165], v[226:229], v[112:115]
	v_mfma_f32_16x16x32_bf16 v[104:107], v[176:179], v[226:229], v[104:107]
	v_mfma_f32_16x16x32_bf16 v[96:99], v[162:165], v[234:237], v[96:99]
	v_mfma_f32_16x16x32_bf16 v[88:91], v[176:179], v[234:237], v[88:91]
	v_mfma_f32_16x16x32_bf16 v[80:83], v[162:165], v[242:245], v[80:83]
	v_mfma_f32_16x16x32_bf16 v[72:75], v[176:179], v[242:245], v[72:75]
	s_setprio 0
	s_setprio 1
	v_mfma_f32_16x16x32_bf16 v[116:119], v[180:183], v[214:217], v[116:119]
	v_mfma_f32_16x16x32_bf16 v[108:111], v[188:191], v[214:217], v[108:111]
	v_mfma_f32_16x16x32_bf16 v[100:103], v[180:183], v[222:225], v[100:103]
	v_mfma_f32_16x16x32_bf16 v[92:95], v[188:191], v[222:225], v[92:95]
	v_mfma_f32_16x16x32_bf16 v[84:87], v[180:183], v[230:233], v[84:87]
	v_mfma_f32_16x16x32_bf16 v[76:79], v[188:191], v[230:233], v[76:79]
	v_mfma_f32_16x16x32_bf16 v[68:71], v[180:183], v[238:241], v[68:71]
	v_mfma_f32_16x16x32_bf16 v[64:67], v[188:191], v[238:241], v[64:67]
	v_mfma_f32_16x16x32_bf16 v[116:119], v[184:187], v[218:221], v[116:119]
	v_mfma_f32_16x16x32_bf16 v[108:111], v[210:213], v[218:221], v[108:111]
	v_mfma_f32_16x16x32_bf16 v[100:103], v[184:187], v[226:229], v[100:103]
	v_mfma_f32_16x16x32_bf16 v[92:95], v[210:213], v[226:229], v[92:95]
	s_setprio 0
	s_barrier
	v_mfma_f32_16x16x32_bf16 v[84:87], v[184:187], v[234:237], v[84:87]
	v_mfma_f32_16x16x32_bf16 v[76:79], v[210:213], v[234:237], v[76:79]
	v_mfma_f32_16x16x32_bf16 v[68:71], v[184:187], v[242:245], v[68:71]
	v_mfma_f32_16x16x32_bf16 v[64:67], v[210:213], v[242:245], v[64:67]
	s_mov_b32 m0, s27
	v_lshl_add_u64 v[170:171], s[2:3], 0, v[132:133]
	s_add_u32 s54, s2, 0x40000
	ds_read_b128 v[214:217], v173 offset:16384
	ds_read_b128 v[218:221], v173 offset:17408
	ds_read_b128 v[222:225], v173 offset:18432
	ds_read_b128 v[226:229], v173 offset:19456
	ds_read_b128 v[230:233], v173 offset:20480
	ds_read_b128 v[234:237], v173 offset:21504
	ds_read_b128 v[238:241], v173 offset:22528
	ds_read_b128 v[242:245], v173 offset:23552
	global_load_lds_dwordx4 v[170:171], off
	v_lshl_add_u64 v[208:209], s[2:3], 0, v[128:129]
	s_mov_b32 m0, s28
	s_addc_u32 s55, s3, 0
	global_load_lds_dwordx4 v[208:209], off
	v_lshl_add_u64 v[246:247], s[54:55], 0, v[132:133]
	s_mov_b32 m0, s29
	v_lshl_add_u64 v[248:249], s[4:5], 0, v[130:131]
	global_load_lds_dwordx4 v[246:247], off
	v_lshl_add_u64 v[246:247], s[54:55], 0, v[128:129]
	s_mov_b32 m0, s30
	s_nop 0
	global_load_lds_dwordx4 v[246:247], off
	v_lshl_add_u64 v[246:247], s[4:5], 0, v[134:135]
	s_mov_b32 m0, s6
	s_nop 0
	global_load_lds_dwordx4 v[246:247], off
	s_mov_b32 m0, s31
	s_nop 0
	global_load_lds_dwordx4 v[248:249], off
	s_waitcnt vmcnt(8)
	s_waitcnt lgkmcnt(0)
	s_barrier
; #define PG8_STAGE(bufoff, gbase, voff) do { _Pragma("unroll") for (int _i = 0; _i < 2; ++_i) \
;         __builtin_amdgcn_global_load_lds((const unsigned*)((const char*)(gbase) + (voff)[_i]), (PG8_LAS unsigned*)(lds + (bufoff) + ldsw + _i * 8192), 16, 0, 0); } while (0)
; #define PG8_LDA(dst, b, h) do { _Pragma("unroll") for (int m = 0; m < 4; ++m) _Pragma("unroll") for (int k = 0; k < 2; ++k) dst[m][k] = *(const PG8_LAS bf16x8*)(lds + PG8_SA(b, h) + aoff + m * 2048 + k * 1024); } while (0)
; #define PG8_LDB(dst, b, h) do { _Pragma("unroll") for (int n = 0; n < 2; ++n) _Pragma("unroll") for (int k = 0; k < 2; ++k) dst[n][k] = *(const PG8_LAS bf16x8*)(lds + PG8_SB(b, h) + boff + n * 2048 + k * 1024); } while (0)
; #define PG8_MMA(ai, bj, At, Bt) do { __builtin_amdgcn_s_setprio(1); _Pragma("unroll") for (int m = 0; m < 4; ++m) _Pragma("unroll") for (int n = 0; n < 2; ++n) _Pragma("unroll") for (int k = 0; k < 2; ++k) \
;         acc[ai][bj][m][n] = __builtin_amdgcn_mfma_f32_16x16x32_bf16(Bt[n][k], At[m][k], acc[ai][bj][m][n], 0, 0, 0); __builtin_amdgcn_s_setprio(0); } while (0)
; #define PG8_WAIT_V(n) asm volatile("s_waitcnt vmcnt(" #n ")" ::: "memory")
; #define PG8_WAIT_L(n) asm volatile("s_waitcnt lgkmcnt(" #n ")" ::: "memory")
; #define PG8_BAR __builtin_amdgcn_s_barrier()
; #define PG8_SCHED __builtin_amdgcn_sched_barrier(0)
; template <class Epi, class Sched, bool ALIGN_EPI = false, bool SP2 = false>
; __device__ __forceinline__ void gemm_phase(PG8_LAS unsigned char* lds, const Gemm g, const Sched& S, const Epi& E) {
;     ...
;             PG8_WAIT_V(8); PG8_WAIT_L(0); PG8_BAR; PG8_MMA(1, 0, At, B0); PG8_MMA(1, 1, At, B1); PG8_BAR; PG8_SCHED;
;             PG8_LDB(B0, 1, 0); PG8_LDB(B1, 1, 1); PG8_SCHED; PG8_LDA(At, 1, 0); PG8_STAGE(PG8_SA(0, 1), a2 + hstep, voffA);
;             PG8_WAIT_V(8); PG8_WAIT_L(0); PG8_BAR; PG8_MMA(0, 0, At, B0); PG8_MMA(0, 1, At, B1); PG8_BAR; PG8_SCHED;
	s_setprio 1
	s_waitcnt lgkmcnt(0)
	v_mfma_f32_16x16x32_bf16 v[60:63], v[140:143], v[214:217], v[60:63]
	v_mfma_f32_16x16x32_bf16 v[56:59], v[166:169], v[214:217], v[56:59]
	v_mfma_f32_16x16x32_bf16 v[48:51], v[140:143], v[222:225], v[48:51]
	v_mfma_f32_16x16x32_bf16 v[40:43], v[166:169], v[222:225], v[40:43]
	v_mfma_f32_16x16x32_bf16 v[32:35], v[140:143], v[230:233], v[32:35]
	v_mfma_f32_16x16x32_bf16 v[24:27], v[166:169], v[230:233], v[24:27]
	v_mfma_f32_16x16x32_bf16 v[16:19], v[140:143], v[238:241], v[16:19]
	v_mfma_f32_16x16x32_bf16 v[8:11], v[166:169], v[238:241], v[8:11]
	v_mfma_f32_16x16x32_bf16 v[60:63], v[162:165], v[218:221], v[60:63]
	v_mfma_f32_16x16x32_bf16 v[56:59], v[176:179], v[218:221], v[56:59]
	v_mfma_f32_16x16x32_bf16 v[48:51], v[162:165], v[226:229], v[48:51]
	v_mfma_f32_16x16x32_bf16 v[40:43], v[176:179], v[226:229], v[40:43]
	v_mfma_f32_16x16x32_bf16 v[32:35], v[162:165], v[234:237], v[32:35]
	v_mfma_f32_16x16x32_bf16 v[24:27], v[176:179], v[234:237], v[24:27]
	v_mfma_f32_16x16x32_bf16 v[16:19], v[162:165], v[242:245], v[16:19]
	v_mfma_f32_16x16x32_bf16 v[8:11], v[176:179], v[242:245], v[8:11]
	s_setprio 0
	s_setprio 1
	v_mfma_f32_16x16x32_bf16 v[52:55], v[180:183], v[214:217], v[52:55]
	v_mfma_f32_16x16x32_bf16 v[44:47], v[188:191], v[214:217], v[44:47]
	v_mfma_f32_16x16x32_bf16 v[36:39], v[180:183], v[222:225], v[36:39]
	v_mfma_f32_16x16x32_bf16 v[28:31], v[188:191], v[222:225], v[28:31]
	v_mfma_f32_16x16x32_bf16 v[20:23], v[180:183], v[230:233], v[20:23]
	v_mfma_f32_16x16x32_bf16 v[12:15], v[188:191], v[230:233], v[12:15]
	v_mfma_f32_16x16x32_bf16 v[4:7], v[180:183], v[238:241], v[4:7]
	v_mfma_f32_16x16x32_bf16 v[0:3], v[188:191], v[238:241], v[0:3]
	v_mfma_f32_16x16x32_bf16 v[52:55], v[184:187], v[218:221], v[52:55]
	v_mfma_f32_16x16x32_bf16 v[44:47], v[210:213], v[218:221], v[44:47]
	v_mfma_f32_16x16x32_bf16 v[36:39], v[184:187], v[226:229], v[36:39]
	v_mfma_f32_16x16x32_bf16 v[28:31], v[210:213], v[226:229], v[28:31]
	s_setprio 0
	s_barrier
	v_mfma_f32_16x16x32_bf16 v[20:23], v[184:187], v[234:237], v[20:23]
	v_mfma_f32_16x16x32_bf16 v[12:15], v[210:213], v[234:237], v[12:15]
	v_mfma_f32_16x16x32_bf16 v[4:7], v[184:187], v[242:245], v[4:7]
	v_mfma_f32_16x16x32_bf16 v[0:3], v[210:213], v[242:245], v[0:3]
	v_or_b32_e32 v140, 0x18000, v174
	v_add_u32_e32 v162, 0x18400, v174
	v_add_u32_e32 v166, 0x18800, v174
	v_add_u32_e32 v175, 0x18c00, v174
	ds_read_b128 v[140:143], v140
	ds_read_b128 v[162:165], v162
	ds_read_b128 v[166:169], v166
	ds_read_b128 v[176:179], v175
	v_or_b32_e32 v175, 0x1c000, v174
	v_add_u32_e32 v184, 0x1c400, v174
	ds_read_b128 v[180:183], v175
	ds_read_b128 v[184:187], v184
	v_add_u32_e32 v175, 0x1c800, v174
	v_add_u32_e32 v210, 0x1cc00, v174
	ds_read_b128 v[188:191], v175
	ds_read_b128 v[210:213], v210
	s_add_u32 s4, s4, 0x40000
	s_addc_u32 s5, s5, 0
	s_mov_b32 m0, s33
	v_lshl_add_u64 v[250:251], s[4:5], 0, v[134:135]
	ds_read_b128 v[214:217], v173 offset:32768
	ds_read_b128 v[218:221], v173 offset:33792
	ds_read_b128 v[222:225], v173 offset:34816
	ds_read_b128 v[226:229], v173 offset:35840
	ds_read_b128 v[230:233], v173 offset:36864
	ds_read_b128 v[234:237], v173 offset:37888
	ds_read_b128 v[238:241], v173 offset:38912
	ds_read_b128 v[242:245], v173 offset:39936
	global_load_lds_dwordx4 v[250:251], off
	v_lshl_add_u64 v[250:251], s[4:5], 0, v[130:131]
	s_mov_b32 m0, s34
	s_nop 0
	global_load_lds_dwordx4 v[250:251], off
	s_waitcnt vmcnt(8)
	s_waitcnt lgkmcnt(0)
	s_barrier
	s_setprio 1
	s_waitcnt lgkmcnt(0)
	v_mfma_f32_16x16x32_bf16 v[124:127], v[140:143], v[214:217], v[124:127]
	v_mfma_f32_16x16x32_bf16 v[120:123], v[166:169], v[214:217], v[120:123]
	v_mfma_f32_16x16x32_bf16 v[112:115], v[140:143], v[222:225], v[112:115]
	v_mfma_f32_16x16x32_bf16 v[104:107], v[166:169], v[222:225], v[104:107]
	v_mfma_f32_16x16x32_bf16 v[96:99], v[140:143], v[230:233], v[96:99]
	v_mfma_f32_16x16x32_bf16 v[88:91], v[166:169], v[230:233], v[88:91]
	v_mfma_f32_16x16x32_bf16 v[80:83], v[140:143], v[238:241], v[80:83]
	v_mfma_f32_16x16x32_bf16 v[72:75], v[166:169], v[238:241], v[72:75]
	v_mfma_f32_16x16x32_bf16 v[124:127], v[162:165], v[218:221], v[124:127]
	v_mfma_f32_16x16x32_bf16 v[120:123], v[176:179], v[218:221], v[120:123]
	v_mfma_f32_16x16x32_bf16 v[112:115], v[162:165], v[226:229], v[112:115]
	v_mfma_f32_16x16x32_bf16 v[104:107], v[176:179], v[226:229], v[104:107]
	v_mfma_f32_16x16x32_bf16 v[96:99], v[162:165], v[234:237], v[96:99]
	v_mfma_f32_16x16x32_bf16 v[88:91], v[176:179], v[234:237], v[88:91]
	v_mfma_f32_16x16x32_bf16 v[80:83], v[162:165], v[242:245], v[80:83]
	v_mfma_f32_16x16x32_bf16 v[72:75], v[176:179], v[242:245], v[72:75]
	s_setprio 0
	s_setprio 1
	v_mfma_f32_16x16x32_bf16 v[116:119], v[180:183], v[214:217], v[116:119]
	v_mfma_f32_16x16x32_bf16 v[108:111], v[188:191], v[214:217], v[108:111]
	v_mfma_f32_16x16x32_bf16 v[100:103], v[180:183], v[222:225], v[100:103]
	v_mfma_f32_16x16x32_bf16 v[92:95], v[188:191], v[222:225], v[92:95]
	v_mfma_f32_16x16x32_bf16 v[84:87], v[180:183], v[230:233], v[84:87]
	v_mfma_f32_16x16x32_bf16 v[76:79], v[188:191], v[230:233], v[76:79]
	v_mfma_f32_16x16x32_bf16 v[68:71], v[180:183], v[238:241], v[68:71]
	v_mfma_f32_16x16x32_bf16 v[64:67], v[188:191], v[238:241], v[64:67]
	v_mfma_f32_16x16x32_bf16 v[116:119], v[184:187], v[218:221], v[116:119]
	v_mfma_f32_16x16x32_bf16 v[108:111], v[210:213], v[218:221], v[108:111]
	v_mfma_f32_16x16x32_bf16 v[100:103], v[184:187], v[226:229], v[100:103]
	v_mfma_f32_16x16x32_bf16 v[92:95], v[210:213], v[226:229], v[92:95]
	s_setprio 0
	s_barrier
; #define PG8_STAGE(bufoff, gbase, voff) do { _Pragma("unroll") for (int _i = 0; _i < 2; ++_i) \
;         __builtin_amdgcn_global_load_lds((const unsigned*)((const char*)(gbase) + (voff)[_i]), (PG8_LAS unsigned*)(lds + (bufoff) + ldsw + _i * 8192), 16, 0, 0); } while (0)
; #define PG8_LDA(dst, b, h) do { _Pragma("unroll") for (int m = 0; m < 4; ++m) _Pragma("unroll") for (int k = 0; k < 2; ++k) dst[m][k] = *(const PG8_LAS bf16x8*)(lds + PG8_SA(b, h) + aoff + m * 2048 + k * 1024); } while (0)
; #define PG8_MMA(ai, bj, At, Bt) do { __builtin_amdgcn_s_setprio(1); _Pragma("unroll") for (int m = 0; m < 4; ++m) _Pragma("unroll") for (int n = 0; n < 2; ++n) _Pragma("unroll") for (int k = 0; k < 2; ++k) \
;         acc[ai][bj][m][n] = __builtin_amdgcn_mfma_f32_16x16x32_bf16(Bt[n][k], At[m][k], acc[ai][bj][m][n], 0, 0, 0); __builtin_amdgcn_s_setprio(0); } while (0)
; #define PG8_WAIT_V(n) asm volatile("s_waitcnt vmcnt(" #n ")" ::: "memory")
; #define PG8_WAIT_L(n) asm volatile("s_waitcnt lgkmcnt(" #n ")" ::: "memory")
; #define PG8_BAR __builtin_amdgcn_s_barrier()
; #define PG8_SCHED __builtin_amdgcn_sched_barrier(0)
; template <class Epi, class Sched, bool ALIGN_EPI = false, bool SP2 = false>
; __device__ __forceinline__ void gemm_phase(PG8_LAS unsigned char* lds, const Gemm g, const Sched& S, const Epi& E) {
;     ...
;             PG8_WAIT_V(8); PG8_WAIT_L(0); PG8_BAR; PG8_MMA(0, 0, At, B0); PG8_MMA(0, 1, At, B1); PG8_BAR; PG8_SCHED;
;             PG8_LDA(At, 1, 1); PG8_STAGE(PG8_SB(1, 0), b3, voffB); PG8_STAGE(PG8_SB(1, 1), b3 + hstep, voffB); PG8_STAGE(PG8_SA(1, 0), a3, voffA);
;             PG8_WAIT_V(8); PG8_WAIT_L(0); PG8_BAR; PG8_MMA(1, 0, At, B0); PG8_MMA(1, 1, At, B1); PG8_BAR; PG8_SCHED;
;     ...
;         if constexpr (ALIGN_EPI) { if (wr == 0) PG8_BAR; }
	v_mfma_f32_16x16x32_bf16 v[84:87], v[184:187], v[234:237], v[84:87]
	v_mfma_f32_16x16x32_bf16 v[76:79], v[210:213], v[234:237], v[76:79]
	v_mfma_f32_16x16x32_bf16 v[68:71], v[184:187], v[242:245], v[68:71]
	v_mfma_f32_16x16x32_bf16 v[64:67], v[210:213], v[242:245], v[64:67]
	s_mov_b32 m0, s37
	v_lshl_add_u64 v[170:171], v[170:171], 0, s[94:95]
	s_add_u32 s2, s2, 0x40080
	ds_read_b128 v[214:217], v173 offset:49152
	ds_read_b128 v[218:221], v173 offset:50176
	ds_read_b128 v[222:225], v173 offset:51200
	ds_read_b128 v[226:229], v173 offset:52224
	ds_read_b128 v[230:233], v173 offset:53248
	ds_read_b128 v[234:237], v173 offset:54272
	ds_read_b128 v[238:241], v173 offset:55296
	ds_read_b128 v[242:245], v173 offset:56320
	global_load_lds_dwordx4 v[170:171], off
	v_lshl_add_u64 v[170:171], v[208:209], 0, s[94:95]
	s_mov_b32 m0, s38
	s_addc_u32 s3, s3, 0
	global_load_lds_dwordx4 v[170:171], off
	v_lshl_add_u64 v[170:171], s[2:3], 0, v[132:133]
	s_mov_b32 m0, s41
	s_nop 0
	global_load_lds_dwordx4 v[170:171], off
	v_lshl_add_u64 v[170:171], s[2:3], 0, v[128:129]
	s_mov_b32 m0, s42
	s_nop 0
	global_load_lds_dwordx4 v[170:171], off
	v_lshl_add_u64 v[170:171], v[246:247], 0, s[94:95]
	s_mov_b32 m0, s39
	s_nop 0
	global_load_lds_dwordx4 v[170:171], off
	v_lshl_add_u64 v[170:171], v[248:249], 0, s[94:95]
	s_mov_b32 m0, s40
	s_nop 0
	global_load_lds_dwordx4 v[170:171], off
	s_waitcnt vmcnt(8)
	s_waitcnt lgkmcnt(0)
	s_barrier
	s_setprio 1
	s_waitcnt lgkmcnt(0)
	v_mfma_f32_16x16x32_bf16 v[60:63], v[140:143], v[214:217], v[60:63]
	v_mfma_f32_16x16x32_bf16 v[56:59], v[166:169], v[214:217], v[56:59]
	v_mfma_f32_16x16x32_bf16 v[48:51], v[140:143], v[222:225], v[48:51]
	v_mfma_f32_16x16x32_bf16 v[40:43], v[166:169], v[222:225], v[40:43]
	v_mfma_f32_16x16x32_bf16 v[32:35], v[140:143], v[230:233], v[32:35]
	v_mfma_f32_16x16x32_bf16 v[24:27], v[166:169], v[230:233], v[24:27]
	v_mfma_f32_16x16x32_bf16 v[16:19], v[140:143], v[238:241], v[16:19]
	v_mfma_f32_16x16x32_bf16 v[8:11], v[166:169], v[238:241], v[8:11]
	v_mfma_f32_16x16x32_bf16 v[60:63], v[162:165], v[218:221], v[60:63]
	v_mfma_f32_16x16x32_bf16 v[56:59], v[176:179], v[218:221], v[56:59]
	v_mfma_f32_16x16x32_bf16 v[48:51], v[162:165], v[226:229], v[48:51]
	v_mfma_f32_16x16x32_bf16 v[40:43], v[176:179], v[226:229], v[40:43]
	v_mfma_f32_16x16x32_bf16 v[32:35], v[162:165], v[234:237], v[32:35]
	v_mfma_f32_16x16x32_bf16 v[24:27], v[176:179], v[234:237], v[24:27]
	v_mfma_f32_16x16x32_bf16 v[16:19], v[162:165], v[242:245], v[16:19]
	v_mfma_f32_16x16x32_bf16 v[8:11], v[176:179], v[242:245], v[8:11]
	s_setprio 0
	s_setprio 1
	v_mfma_f32_16x16x32_bf16 v[52:55], v[180:183], v[214:217], v[52:55]
	v_mfma_f32_16x16x32_bf16 v[44:47], v[188:191], v[214:217], v[44:47]
	v_mfma_f32_16x16x32_bf16 v[36:39], v[180:183], v[222:225], v[36:39]
	v_mfma_f32_16x16x32_bf16 v[28:31], v[188:191], v[222:225], v[28:31]
	v_mfma_f32_16x16x32_bf16 v[20:23], v[180:183], v[230:233], v[20:23]
	v_mfma_f32_16x16x32_bf16 v[12:15], v[188:191], v[230:233], v[12:15]
	v_mfma_f32_16x16x32_bf16 v[4:7], v[180:183], v[238:241], v[4:7]
	v_mfma_f32_16x16x32_bf16 v[0:3], v[188:191], v[238:241], v[0:3]
	v_mfma_f32_16x16x32_bf16 v[52:55], v[184:187], v[218:221], v[52:55]
	v_mfma_f32_16x16x32_bf16 v[44:47], v[210:213], v[218:221], v[44:47]
	v_mfma_f32_16x16x32_bf16 v[36:39], v[184:187], v[226:229], v[36:39]
	v_mfma_f32_16x16x32_bf16 v[28:31], v[210:213], v[226:229], v[28:31]
	s_setprio 0
	s_barrier
	v_mfma_f32_16x16x32_bf16 v[20:23], v[184:187], v[234:237], v[20:23]
	v_mfma_f32_16x16x32_bf16 v[12:15], v[210:213], v[234:237], v[12:15]
	v_mfma_f32_16x16x32_bf16 v[4:7], v[184:187], v[242:245], v[4:7]
	v_mfma_f32_16x16x32_bf16 v[0:3], v[210:213], v[242:245], v[0:3]
	s_add_i32 s52, s52, 2
	s_add_u32 s0, s0, 0x100
	s_addc_u32 s1, s1, 0
	s_add_u32 s50, s50, 0x100
	s_addc_u32 s51, s51, 0
	s_cmp_gt_u32 s52, 13
	s_cbranch_scc0 .LBB0_792
	s_and_b64 vcc, exec, s[12:13]
	s_cbranch_vccz .LBB0_795
	s_barrier

; #define PG8_STAGE(bufoff, gbase, voff) do { _Pragma("unroll") for (int _i = 0; _i < 2; ++_i) \
;         __builtin_amdgcn_global_load_lds((const unsigned*)((const char*)(gbase) + (voff)[_i]), (PG8_LAS unsigned*)(lds + (bufoff) + ldsw + _i * 8192), 16, 0, 0); } while (0)
; #define PG8_LDA(dst, b, h) do { _Pragma("unroll") for (int m = 0; m < 4; ++m) _Pragma("unroll") for (int k = 0; k < 2; ++k) dst[m][k] = *(const PG8_LAS bf16x8*)(lds + PG8_SA(b, h) + aoff + m * 2048 + k * 1024); } while (0)
; #define PG8_LDB(dst, b, h) do { _Pragma("unroll") for (int n = 0; n < 2; ++n) _Pragma("unroll") for (int k = 0; k < 2; ++k) dst[n][k] = *(const PG8_LAS bf16x8*)(lds + PG8_SB(b, h) + boff + n * 2048 + k * 1024); } while (0)
; #define PG8_MMA(ai, bj, At, Bt) do { __builtin_amdgcn_s_setprio(1); _Pragma("unroll") for (int m = 0; m < 4; ++m) _Pragma("unroll") for (int n = 0; n < 2; ++n) _Pragma("unroll") for (int k = 0; k < 2; ++k) \
;         acc[ai][bj][m][n] = __builtin_amdgcn_mfma_f32_16x16x32_bf16(Bt[n][k], At[m][k], acc[ai][bj][m][n], 0, 0, 0); __builtin_amdgcn_s_setprio(0); } while (0)
; #define PG8_WAIT_V(n) asm volatile("s_waitcnt vmcnt(" #n ")" ::: "memory")
; #define PG8_WAIT_L(n) asm volatile("s_waitcnt lgkmcnt(" #n ")" ::: "memory")
; #define PG8_BAR __builtin_amdgcn_s_barrier()
; #define PG8_SCHED __builtin_amdgcn_sched_barrier(0)
; template <class Epi, class Sched, bool ALIGN_EPI = false, bool SP2 = false>
; __device__ __forceinline__ void gemm_phase(PG8_LAS unsigned char* lds, const Gemm g, const Sched& S, const Epi& E) {
;     ...
;             PG8_LDB(B0, 0, 0); PG8_LDB(B1, 0, 1); PG8_SCHED; PG8_LDA(At, 0, 0); PG8_STAGE(PG8_SA(1, 1), a1 + hstep, voffA);
;             PG8_WAIT_V(8); PG8_WAIT_L(0); PG8_BAR; PG8_MMA(0, 0, At, B0); PG8_MMA(0, 1, At, B1); PG8_BAR; PG8_SCHED;
;             PG8_LDA(At, 0, 1); PG8_STAGE(PG8_SB(0, 0), b2, voffB); PG8_STAGE(PG8_SB(0, 1), b2 + hstep, voffB); PG8_STAGE(PG8_SA(0, 0), a2, voffA);
;             PG8_WAIT_V(8); PG8_WAIT_L(0); PG8_BAR; PG8_MMA(1, 0, At, B0); PG8_MMA(1, 1, At, B1); PG8_BAR; PG8_SCHED;
.LBB0_1042:
	v_or_b32_e32 v140, 0x10000, v164
	v_add_u32_e32 v165, 0x10400, v164
	ds_read_b128 v[140:143], v140
	ds_read_b128 v[166:169], v165
	v_add_u32_e32 v165, 0x10800, v164
	v_add_u32_e32 v174, 0x10c00, v164
	ds_read_b128 v[170:173], v165
	ds_read_b128 v[174:177], v174
	v_or_b32_e32 v165, 0x14000, v164
	v_add_u32_e32 v182, 0x14400, v164
	ds_read_b128 v[178:181], v165
	ds_read_b128 v[182:185], v182
	v_add_u32_e32 v165, 0x14800, v164
	v_add_u32_e32 v190, 0x14c00, v164
	ds_read_b128 v[186:189], v165
	ds_read_b128 v[210:213], v190
	s_add_u32 s2, s0, 0xfffc0080
	s_addc_u32 s3, s1, -1
	s_cmp_eq_u32 s55, 12
	s_cselect_b32 s5, s23, s3
	s_cselect_b32 s4, s51, s2
	s_cselect_b32 s3, s21, s54
	s_cselect_b32 s2, s52, s53
	v_lshl_add_u64 v[190:191], s[0:1], 0, v[136:137]
	s_add_i32 m0, s31, 0xc000
	ds_read_b128 v[214:217], v163
	ds_read_b128 v[218:221], v163 offset:1024
	ds_read_b128 v[222:225], v163 offset:2048
	ds_read_b128 v[226:229], v163 offset:3072
	ds_read_b128 v[230:233], v163 offset:4096
	ds_read_b128 v[234:237], v163 offset:5120
	ds_read_b128 v[238:241], v163 offset:6144
	ds_read_b128 v[242:245], v163 offset:7168
	global_load_lds_dwordx4 v[190:191], off
	v_lshl_add_u64 v[190:191], s[0:1], 0, v[138:139]
	s_add_i32 m0, s31, 0xe000
	s_nop 0
	global_load_lds_dwordx4 v[190:191], off
	s_waitcnt vmcnt(8)
	s_waitcnt lgkmcnt(0)
	s_barrier
	s_setprio 1
	s_waitcnt lgkmcnt(0)
	v_mfma_f32_16x16x32_bf16 v[124:127], v[140:143], v[214:217], v[124:127]
	v_mfma_f32_16x16x32_bf16 v[120:123], v[170:173], v[214:217], v[120:123]
	v_mfma_f32_16x16x32_bf16 v[108:111], v[140:143], v[222:225], v[108:111]
	v_mfma_f32_16x16x32_bf16 v[104:107], v[170:173], v[222:225], v[104:107]
	v_mfma_f32_16x16x32_bf16 v[92:95], v[140:143], v[230:233], v[92:95]
	v_mfma_f32_16x16x32_bf16 v[88:91], v[170:173], v[230:233], v[88:91]
	v_mfma_f32_16x16x32_bf16 v[76:79], v[140:143], v[238:241], v[76:79]
	v_mfma_f32_16x16x32_bf16 v[72:75], v[170:173], v[238:241], v[72:75]
	v_mfma_f32_16x16x32_bf16 v[124:127], v[166:169], v[218:221], v[124:127]
	v_mfma_f32_16x16x32_bf16 v[120:123], v[174:177], v[218:221], v[120:123]
	v_mfma_f32_16x16x32_bf16 v[108:111], v[166:169], v[226:229], v[108:111]
	v_mfma_f32_16x16x32_bf16 v[104:107], v[174:177], v[226:229], v[104:107]
	v_mfma_f32_16x16x32_bf16 v[92:95], v[166:169], v[234:237], v[92:95]
	v_mfma_f32_16x16x32_bf16 v[88:91], v[174:177], v[234:237], v[88:91]
	v_mfma_f32_16x16x32_bf16 v[76:79], v[166:169], v[242:245], v[76:79]
	v_mfma_f32_16x16x32_bf16 v[72:75], v[174:177], v[242:245], v[72:75]
	s_setprio 0
	s_setprio 1
	v_mfma_f32_16x16x32_bf16 v[116:119], v[178:181], v[214:217], v[116:119]
	v_mfma_f32_16x16x32_bf16 v[112:115], v[186:189], v[214:217], v[112:115]
	v_mfma_f32_16x16x32_bf16 v[100:103], v[178:181], v[222:225], v[100:103]
	v_mfma_f32_16x16x32_bf16 v[96:99], v[186:189], v[222:225], v[96:99]
	v_mfma_f32_16x16x32_bf16 v[84:87], v[178:181], v[230:233], v[84:87]
	v_mfma_f32_16x16x32_bf16 v[80:83], v[186:189], v[230:233], v[80:83]
	v_mfma_f32_16x16x32_bf16 v[68:71], v[178:181], v[238:241], v[68:71]
	v_mfma_f32_16x16x32_bf16 v[64:67], v[186:189], v[238:241], v[64:67]
	v_mfma_f32_16x16x32_bf16 v[116:119], v[182:185], v[218:221], v[116:119]
	v_mfma_f32_16x16x32_bf16 v[112:115], v[210:213], v[218:221], v[112:115]
	v_mfma_f32_16x16x32_bf16 v[100:103], v[182:185], v[226:229], v[100:103]
	v_mfma_f32_16x16x32_bf16 v[96:99], v[210:213], v[226:229], v[96:99]
	s_setprio 0
	s_barrier
	v_mfma_f32_16x16x32_bf16 v[84:87], v[182:185], v[234:237], v[84:87]
	v_mfma_f32_16x16x32_bf16 v[80:83], v[210:213], v[234:237], v[80:83]
	v_mfma_f32_16x16x32_bf16 v[68:71], v[182:185], v[242:245], v[68:71]
	v_mfma_f32_16x16x32_bf16 v[64:67], v[210:213], v[242:245], v[64:67]
	s_mov_b32 m0, s33
	v_lshl_add_u64 v[190:191], s[2:3], 0, v[132:133]
	s_add_u32 s56, s2, 0x40000
	ds_read_b128 v[214:217], v163 offset:16384
	ds_read_b128 v[218:221], v163 offset:17408
	ds_read_b128 v[222:225], v163 offset:18432
	ds_read_b128 v[226:229], v163 offset:19456
	ds_read_b128 v[230:233], v163 offset:20480
	ds_read_b128 v[234:237], v163 offset:21504
	ds_read_b128 v[238:241], v163 offset:22528
	ds_read_b128 v[242:245], v163 offset:23552
	global_load_lds_dwordx4 v[190:191], off
	v_lshl_add_u64 v[208:209], s[2:3], 0, v[128:129]
	s_mov_b32 m0, s34
	s_addc_u32 s57, s3, 0
	global_load_lds_dwordx4 v[208:209], off
	v_lshl_add_u64 v[246:247], s[56:57], 0, v[132:133]
	s_mov_b32 m0, s35
	v_lshl_add_u64 v[248:249], s[4:5], 0, v[130:131]
	global_load_lds_dwordx4 v[246:247], off
	v_lshl_add_u64 v[246:247], s[56:57], 0, v[128:129]
	s_mov_b32 m0, s36
	s_nop 0
	global_load_lds_dwordx4 v[246:247], off
	v_lshl_add_u64 v[246:247], s[4:5], 0, v[134:135]
	s_mov_b32 m0, s31
	s_nop 0
	global_load_lds_dwordx4 v[246:247], off
	s_mov_b32 m0, s37
	s_nop 0
	global_load_lds_dwordx4 v[248:249], off
	s_waitcnt vmcnt(8)
	s_waitcnt lgkmcnt(0)
	s_barrier
; #define PG8_STAGE(bufoff, gbase, voff) do { _Pragma("unroll") for (int _i = 0; _i < 2; ++_i) \
;         __builtin_amdgcn_global_load_lds((const unsigned*)((const char*)(gbase) + (voff)[_i]), (PG8_LAS unsigned*)(lds + (bufoff) + ldsw + _i * 8192), 16, 0, 0); } while (0)
; #define PG8_LDA(dst, b, h) do { _Pragma("unroll") for (int m = 0; m < 4; ++m) _Pragma("unroll") for (int k = 0; k < 2; ++k) dst[m][k] = *(const PG8_LAS bf16x8*)(lds + PG8_SA(b, h) + aoff + m * 2048 + k * 1024); } while (0)
; #define PG8_LDB(dst, b, h) do { _Pragma("unroll") for (int n = 0; n < 2; ++n) _Pragma("unroll") for (int k = 0; k < 2; ++k) dst[n][k] = *(const PG8_LAS bf16x8*)(lds + PG8_SB(b, h) + boff + n * 2048 + k * 1024); } while (0)
; #define PG8_MMA(ai, bj, At, Bt) do { __builtin_amdgcn_s_setprio(1); _Pragma("unroll") for (int m = 0; m < 4; ++m) _Pragma("unroll") for (int n = 0; n < 2; ++n) _Pragma("unroll") for (int k = 0; k < 2; ++k) \
;         acc[ai][bj][m][n] = __builtin_amdgcn_mfma_f32_16x16x32_bf16(Bt[n][k], At[m][k], acc[ai][bj][m][n], 0, 0, 0); __builtin_amdgcn_s_setprio(0); } while (0)
; #define PG8_WAIT_V(n) asm volatile("s_waitcnt vmcnt(" #n ")" ::: "memory")
; #define PG8_WAIT_L(n) asm volatile("s_waitcnt lgkmcnt(" #n ")" ::: "memory")
; #define PG8_BAR __builtin_amdgcn_s_barrier()
; #define PG8_SCHED __builtin_amdgcn_sched_barrier(0)
; template <class Epi, class Sched, bool ALIGN_EPI = false, bool SP2 = false>
; __device__ __forceinline__ void gemm_phase(PG8_LAS unsigned char* lds, const Gemm g, const Sched& S, const Epi& E) {
;     ...
;             PG8_WAIT_V(8); PG8_WAIT_L(0); PG8_BAR; PG8_MMA(1, 0, At, B0); PG8_MMA(1, 1, At, B1); PG8_BAR; PG8_SCHED;
;             PG8_LDB(B0, 1, 0); PG8_LDB(B1, 1, 1); PG8_SCHED; PG8_LDA(At, 1, 0); PG8_STAGE(PG8_SA(0, 1), a2 + hstep, voffA);
;             PG8_WAIT_V(8); PG8_WAIT_L(0); PG8_BAR; PG8_MMA(0, 0, At, B0); PG8_MMA(0, 1, At, B1); PG8_BAR; PG8_SCHED;
	s_setprio 1
	s_waitcnt lgkmcnt(0)
	v_mfma_f32_16x16x32_bf16 v[60:63], v[140:143], v[214:217], v[60:63]
	v_mfma_f32_16x16x32_bf16 v[56:59], v[170:173], v[214:217], v[56:59]
	v_mfma_f32_16x16x32_bf16 v[44:47], v[140:143], v[222:225], v[44:47]
	v_mfma_f32_16x16x32_bf16 v[40:43], v[170:173], v[222:225], v[40:43]
	v_mfma_f32_16x16x32_bf16 v[28:31], v[140:143], v[230:233], v[28:31]
	v_mfma_f32_16x16x32_bf16 v[24:27], v[170:173], v[230:233], v[24:27]
	v_mfma_f32_16x16x32_bf16 v[12:15], v[140:143], v[238:241], v[12:15]
	v_mfma_f32_16x16x32_bf16 v[8:11], v[170:173], v[238:241], v[8:11]
	v_mfma_f32_16x16x32_bf16 v[60:63], v[166:169], v[218:221], v[60:63]
	v_mfma_f32_16x16x32_bf16 v[56:59], v[174:177], v[218:221], v[56:59]
	v_mfma_f32_16x16x32_bf16 v[44:47], v[166:169], v[226:229], v[44:47]
	v_mfma_f32_16x16x32_bf16 v[40:43], v[174:177], v[226:229], v[40:43]
	v_mfma_f32_16x16x32_bf16 v[28:31], v[166:169], v[234:237], v[28:31]
	v_mfma_f32_16x16x32_bf16 v[24:27], v[174:177], v[234:237], v[24:27]
	v_mfma_f32_16x16x32_bf16 v[12:15], v[166:169], v[242:245], v[12:15]
	v_mfma_f32_16x16x32_bf16 v[8:11], v[174:177], v[242:245], v[8:11]
	s_setprio 0
	s_setprio 1
	v_mfma_f32_16x16x32_bf16 v[52:55], v[178:181], v[214:217], v[52:55]
	v_mfma_f32_16x16x32_bf16 v[48:51], v[186:189], v[214:217], v[48:51]
	v_mfma_f32_16x16x32_bf16 v[36:39], v[178:181], v[222:225], v[36:39]
	v_mfma_f32_16x16x32_bf16 v[32:35], v[186:189], v[222:225], v[32:35]
	v_mfma_f32_16x16x32_bf16 v[20:23], v[178:181], v[230:233], v[20:23]
	v_mfma_f32_16x16x32_bf16 v[16:19], v[186:189], v[230:233], v[16:19]
	v_mfma_f32_16x16x32_bf16 v[4:7], v[178:181], v[238:241], v[4:7]
	v_mfma_f32_16x16x32_bf16 v[0:3], v[186:189], v[238:241], v[0:3]
	v_mfma_f32_16x16x32_bf16 v[52:55], v[182:185], v[218:221], v[52:55]
	v_mfma_f32_16x16x32_bf16 v[48:51], v[210:213], v[218:221], v[48:51]
	v_mfma_f32_16x16x32_bf16 v[36:39], v[182:185], v[226:229], v[36:39]
	v_mfma_f32_16x16x32_bf16 v[32:35], v[210:213], v[226:229], v[32:35]
	s_setprio 0
	s_barrier
	v_mfma_f32_16x16x32_bf16 v[20:23], v[182:185], v[234:237], v[20:23]
	v_mfma_f32_16x16x32_bf16 v[16:19], v[210:213], v[234:237], v[16:19]
	v_mfma_f32_16x16x32_bf16 v[4:7], v[182:185], v[242:245], v[4:7]
	v_mfma_f32_16x16x32_bf16 v[0:3], v[210:213], v[242:245], v[0:3]
	v_or_b32_e32 v140, 0x18000, v164
	v_add_u32_e32 v165, 0x18400, v164
	ds_read_b128 v[140:143], v140
	ds_read_b128 v[166:169], v165
	v_add_u32_e32 v165, 0x18800, v164
	v_add_u32_e32 v174, 0x18c00, v164
	ds_read_b128 v[170:173], v165
	ds_read_b128 v[174:177], v174
	v_or_b32_e32 v165, 0x1c000, v164
	v_add_u32_e32 v182, 0x1c400, v164
	ds_read_b128 v[178:181], v165
	ds_read_b128 v[182:185], v182
	v_add_u32_e32 v165, 0x1c800, v164
	v_add_u32_e32 v210, 0x1cc00, v164
	ds_read_b128 v[186:189], v165
	ds_read_b128 v[210:213], v210
	s_add_u32 s4, s4, 0x40000
	s_addc_u32 s5, s5, 0
	s_mov_b32 m0, s38
	v_lshl_add_u64 v[250:251], s[4:5], 0, v[134:135]
	ds_read_b128 v[214:217], v163 offset:32768
	ds_read_b128 v[218:221], v163 offset:33792
	ds_read_b128 v[222:225], v163 offset:34816
	ds_read_b128 v[226:229], v163 offset:35840
	ds_read_b128 v[230:233], v163 offset:36864
	ds_read_b128 v[234:237], v163 offset:37888
	ds_read_b128 v[238:241], v163 offset:38912
	ds_read_b128 v[242:245], v163 offset:39936
	global_load_lds_dwordx4 v[250:251], off
	v_lshl_add_u64 v[250:251], s[4:5], 0, v[130:131]
	s_mov_b32 m0, s39
	s_nop 0
	global_load_lds_dwordx4 v[250:251], off
	s_waitcnt vmcnt(8)
	s_waitcnt lgkmcnt(0)
	s_barrier
	s_setprio 1
	s_waitcnt lgkmcnt(0)
	v_mfma_f32_16x16x32_bf16 v[124:127], v[140:143], v[214:217], v[124:127]
	v_mfma_f32_16x16x32_bf16 v[120:123], v[170:173], v[214:217], v[120:123]
	v_mfma_f32_16x16x32_bf16 v[108:111], v[140:143], v[222:225], v[108:111]
	v_mfma_f32_16x16x32_bf16 v[104:107], v[170:173], v[222:225], v[104:107]
	v_mfma_f32_16x16x32_bf16 v[92:95], v[140:143], v[230:233], v[92:95]
	v_mfma_f32_16x16x32_bf16 v[88:91], v[170:173], v[230:233], v[88:91]
	v_mfma_f32_16x16x32_bf16 v[76:79], v[140:143], v[238:241], v[76:79]
	v_mfma_f32_16x16x32_bf16 v[72:75], v[170:173], v[238:241], v[72:75]
	v_mfma_f32_16x16x32_bf16 v[124:127], v[166:169], v[218:221], v[124:127]
	v_mfma_f32_16x16x32_bf16 v[120:123], v[174:177], v[218:221], v[120:123]
	v_mfma_f32_16x16x32_bf16 v[108:111], v[166:169], v[226:229], v[108:111]
	v_mfma_f32_16x16x32_bf16 v[104:107], v[174:177], v[226:229], v[104:107]
	v_mfma_f32_16x16x32_bf16 v[92:95], v[166:169], v[234:237], v[92:95]
	v_mfma_f32_16x16x32_bf16 v[88:91], v[174:177], v[234:237], v[88:91]
	v_mfma_f32_16x16x32_bf16 v[76:79], v[166:169], v[242:245], v[76:79]
	v_mfma_f32_16x16x32_bf16 v[72:75], v[174:177], v[242:245], v[72:75]
	s_setprio 0
	s_setprio 1
	v_mfma_f32_16x16x32_bf16 v[116:119], v[178:181], v[214:217], v[116:119]
	v_mfma_f32_16x16x32_bf16 v[112:115], v[186:189], v[214:217], v[112:115]
	v_mfma_f32_16x16x32_bf16 v[100:103], v[178:181], v[222:225], v[100:103]
	v_mfma_f32_16x16x32_bf16 v[96:99], v[186:189], v[222:225], v[96:99]
	v_mfma_f32_16x16x32_bf16 v[84:87], v[178:181], v[230:233], v[84:87]
	v_mfma_f32_16x16x32_bf16 v[80:83], v[186:189], v[230:233], v[80:83]
	v_mfma_f32_16x16x32_bf16 v[68:71], v[178:181], v[238:241], v[68:71]
	v_mfma_f32_16x16x32_bf16 v[64:67], v[186:189], v[238:241], v[64:67]
	v_mfma_f32_16x16x32_bf16 v[116:119], v[182:185], v[218:221], v[116:119]
	v_mfma_f32_16x16x32_bf16 v[112:115], v[210:213], v[218:221], v[112:115]
	v_mfma_f32_16x16x32_bf16 v[100:103], v[182:185], v[226:229], v[100:103]
	v_mfma_f32_16x16x32_bf16 v[96:99], v[210:213], v[226:229], v[96:99]
	s_setprio 0
	s_barrier
; #define PG8_STAGE(bufoff, gbase, voff) do { _Pragma("unroll") for (int _i = 0; _i < 2; ++_i) \
;         __builtin_amdgcn_global_load_lds((const unsigned*)((const char*)(gbase) + (voff)[_i]), (PG8_LAS unsigned*)(lds + (bufoff) + ldsw + _i * 8192), 16, 0, 0); } while (0)
; #define PG8_LDA(dst, b, h) do { _Pragma("unroll") for (int m = 0; m < 4; ++m) _Pragma("unroll") for (int k = 0; k < 2; ++k) dst[m][k] = *(const PG8_LAS bf16x8*)(lds + PG8_SA(b, h) + aoff + m * 2048 + k * 1024); } while (0)
; #define PG8_MMA(ai, bj, At, Bt) do { __builtin_amdgcn_s_setprio(1); _Pragma("unroll") for (int m = 0; m < 4; ++m) _Pragma("unroll") for (int n = 0; n < 2; ++n) _Pragma("unroll") for (int k = 0; k < 2; ++k) \
;         acc[ai][bj][m][n] = __builtin_amdgcn_mfma_f32_16x16x32_bf16(Bt[n][k], At[m][k], acc[ai][bj][m][n], 0, 0, 0); __builtin_amdgcn_s_setprio(0); } while (0)
; #define PG8_WAIT_V(n) asm volatile("s_waitcnt vmcnt(" #n ")" ::: "memory")
; #define PG8_WAIT_L(n) asm volatile("s_waitcnt lgkmcnt(" #n ")" ::: "memory")
; #define PG8_BAR __builtin_amdgcn_s_barrier()
; #define PG8_SCHED __builtin_amdgcn_sched_barrier(0)
; template <class Epi, class Sched, bool ALIGN_EPI = false, bool SP2 = false>
; __device__ __forceinline__ void gemm_phase(PG8_LAS unsigned char* lds, const Gemm g, const Sched& S, const Epi& E) {
;     ...
;             PG8_WAIT_V(8); PG8_WAIT_L(0); PG8_BAR; PG8_MMA(0, 0, At, B0); PG8_MMA(0, 1, At, B1); PG8_BAR; PG8_SCHED;
;             PG8_LDA(At, 1, 1); PG8_STAGE(PG8_SB(1, 0), b3, voffB); PG8_STAGE(PG8_SB(1, 1), b3 + hstep, voffB); PG8_STAGE(PG8_SA(1, 0), a3, voffA);
;             PG8_WAIT_V(8); PG8_WAIT_L(0); PG8_BAR; PG8_MMA(1, 0, At, B0); PG8_MMA(1, 1, At, B1); PG8_BAR; PG8_SCHED;
;     ...
;         if constexpr (ALIGN_EPI) { if (wr == 0) PG8_BAR; }
	v_mfma_f32_16x16x32_bf16 v[84:87], v[182:185], v[234:237], v[84:87]
	v_mfma_f32_16x16x32_bf16 v[80:83], v[210:213], v[234:237], v[80:83]
	v_mfma_f32_16x16x32_bf16 v[68:71], v[182:185], v[242:245], v[68:71]
	v_mfma_f32_16x16x32_bf16 v[64:67], v[210:213], v[242:245], v[64:67]
	s_mov_b32 m0, s43
	v_lshl_add_u64 v[190:191], v[190:191], 0, s[94:95]
	s_add_u32 s2, s2, 0x40080
	ds_read_b128 v[214:217], v163 offset:49152
	ds_read_b128 v[218:221], v163 offset:50176
	ds_read_b128 v[222:225], v163 offset:51200
	ds_read_b128 v[226:229], v163 offset:52224
	ds_read_b128 v[230:233], v163 offset:53248
	ds_read_b128 v[234:237], v163 offset:54272
	ds_read_b128 v[238:241], v163 offset:55296
	ds_read_b128 v[242:245], v163 offset:56320
	global_load_lds_dwordx4 v[190:191], off
	v_lshl_add_u64 v[190:191], v[208:209], 0, s[94:95]
	s_mov_b32 m0, s44
	s_addc_u32 s3, s3, 0
	global_load_lds_dwordx4 v[190:191], off
	v_lshl_add_u64 v[190:191], s[2:3], 0, v[132:133]
	s_mov_b32 m0, s48
	s_nop 0
	global_load_lds_dwordx4 v[190:191], off
	v_lshl_add_u64 v[190:191], s[2:3], 0, v[128:129]
	s_mov_b32 m0, s49
	s_nop 0
	global_load_lds_dwordx4 v[190:191], off
	v_lshl_add_u64 v[190:191], v[246:247], 0, s[94:95]
	s_mov_b32 m0, s45
	s_nop 0
	global_load_lds_dwordx4 v[190:191], off
	v_lshl_add_u64 v[190:191], v[248:249], 0, s[94:95]
	s_mov_b32 m0, s47
	s_nop 0
	global_load_lds_dwordx4 v[190:191], off
	s_waitcnt vmcnt(8)
	s_waitcnt lgkmcnt(0)
	s_barrier
	s_setprio 1
	s_waitcnt lgkmcnt(0)
	v_mfma_f32_16x16x32_bf16 v[60:63], v[140:143], v[214:217], v[60:63]
	v_mfma_f32_16x16x32_bf16 v[56:59], v[170:173], v[214:217], v[56:59]
	v_mfma_f32_16x16x32_bf16 v[44:47], v[140:143], v[222:225], v[44:47]
	v_mfma_f32_16x16x32_bf16 v[40:43], v[170:173], v[222:225], v[40:43]
	v_mfma_f32_16x16x32_bf16 v[28:31], v[140:143], v[230:233], v[28:31]
	v_mfma_f32_16x16x32_bf16 v[24:27], v[170:173], v[230:233], v[24:27]
	v_mfma_f32_16x16x32_bf16 v[12:15], v[140:143], v[238:241], v[12:15]
	v_mfma_f32_16x16x32_bf16 v[8:11], v[170:173], v[238:241], v[8:11]
	v_mfma_f32_16x16x32_bf16 v[60:63], v[166:169], v[218:221], v[60:63]
	v_mfma_f32_16x16x32_bf16 v[56:59], v[174:177], v[218:221], v[56:59]
	v_mfma_f32_16x16x32_bf16 v[44:47], v[166:169], v[226:229], v[44:47]
	v_mfma_f32_16x16x32_bf16 v[40:43], v[174:177], v[226:229], v[40:43]
	v_mfma_f32_16x16x32_bf16 v[28:31], v[166:169], v[234:237], v[28:31]
	v_mfma_f32_16x16x32_bf16 v[24:27], v[174:177], v[234:237], v[24:27]
	v_mfma_f32_16x16x32_bf16 v[12:15], v[166:169], v[242:245], v[12:15]
	v_mfma_f32_16x16x32_bf16 v[8:11], v[174:177], v[242:245], v[8:11]
	s_setprio 0
	s_setprio 1
	v_mfma_f32_16x16x32_bf16 v[52:55], v[178:181], v[214:217], v[52:55]
	v_mfma_f32_16x16x32_bf16 v[48:51], v[186:189], v[214:217], v[48:51]
	v_mfma_f32_16x16x32_bf16 v[36:39], v[178:181], v[222:225], v[36:39]
	v_mfma_f32_16x16x32_bf16 v[32:35], v[186:189], v[222:225], v[32:35]
	v_mfma_f32_16x16x32_bf16 v[20:23], v[178:181], v[230:233], v[20:23]
	v_mfma_f32_16x16x32_bf16 v[16:19], v[186:189], v[230:233], v[16:19]
	v_mfma_f32_16x16x32_bf16 v[4:7], v[178:181], v[238:241], v[4:7]
	v_mfma_f32_16x16x32_bf16 v[0:3], v[186:189], v[238:241], v[0:3]
	v_mfma_f32_16x16x32_bf16 v[52:55], v[182:185], v[218:221], v[52:55]
	v_mfma_f32_16x16x32_bf16 v[48:51], v[210:213], v[218:221], v[48:51]
	v_mfma_f32_16x16x32_bf16 v[36:39], v[182:185], v[226:229], v[36:39]
	v_mfma_f32_16x16x32_bf16 v[32:35], v[210:213], v[226:229], v[32:35]
	s_setprio 0
	s_barrier
	v_mfma_f32_16x16x32_bf16 v[20:23], v[182:185], v[234:237], v[20:23]
	v_mfma_f32_16x16x32_bf16 v[16:19], v[210:213], v[234:237], v[16:19]
	v_mfma_f32_16x16x32_bf16 v[4:7], v[182:185], v[242:245], v[4:7]
	v_mfma_f32_16x16x32_bf16 v[0:3], v[210:213], v[242:245], v[0:3]
	s_add_i32 s55, s55, 2
	s_add_u32 s0, s0, 0x100
	s_addc_u32 s1, s1, 0
	s_add_u32 s53, s53, 0x100
	s_addc_u32 s54, s54, 0
	s_cmp_gt_u32 s55, 13
	s_cbranch_scc0 .LBB0_1042
	s_and_b64 vcc, exec, s[18:19]
	s_cbranch_vccz .LBB0_1045
	s_barrier
